# G2 recurrence loop hand-written with next-chunk prefetch; conv and final LayerNorm cross-lane sums via DPP row operations (same addition tree)
# speedup vs baseline: 1.0472x; 1.0059x over previous
; __device__ __forceinline__ bf16_t f2bf(float f) { unsigned u = __float_as_uint(f); return (bf16_t)((u + 0x7fffu + ((u >> 16) & 1u)) >> 16); }
; __device__ __forceinline__ void gla_g2_phase(const float* UPD, bf16_t* SP, const float* DEC, int G, int tid) {
;     for (int g = blockIdx.x * 512 + tid; g < 16 * 8192; g += G * 512) {
;         const int bh = g >> 13, ed = g & 8191, d = g & 63;
;         const float* p = UPD + (size_t)bh * 128 * 8192 + ed; bf16_t* po = SP + (size_t)bh * 128 * 8192 + ed; const float* dc = DEC + bh * 128 * 64 + d;
;         float S = 0.f;
;         for (int n0 = 0; n0 < 128; n0 += 16) { float uu[16], dd[16];
; #pragma unroll
;             for (int x = 0; x < 16; ++x) { uu[x] = p[(size_t)(n0 + x) * 8192]; dd[x] = dc[(n0 + x) * 64]; }
; #pragma unroll
;             for (int x = 0; x < 16; ++x) { po[(size_t)(n0 + x) * 8192] = f2bf(S); S = dd[x] * S + uu[x]; } }
.LBB0_422:
	v_ashrrev_i32_e32 v6, 13, v1
	v_and_b32_e32 v2, 0xffffe000, v1
	v_ashrrev_i32_e32 v7, 31, v6
	v_ashrrev_i32_e32 v3, 31, v2
	v_and_b32_e32 v9, 0x1fff, v8
	v_lshlrev_b64 v[4:5], 22, v[6:7]
	v_lshlrev_b64 v[6:7], 21, v[6:7]
	v_readlane_b32 s6, v253, 20
	v_lshlrev_b64 v[2:3], 2, v[2:3]
	v_lshl_or_b32 v6, v9, 1, v6
	v_readlane_b32 s7, v253, 21
	v_or_b32_e32 v2, v0, v2
	v_lshl_or_b32 v4, v9, 2, v4
	v_lshl_add_u64 v[6:7], s[6:7], 0, v[6:7]
	v_mov_b32_e32 v16, 0
	s_mov_b32 s6, -16
	s_mov_b64 s[12:13], 0x40000
	s_mov_b64 s[14:15], 0x1000
	s_mov_b64 s[10:11], 0x8000
	s_mov_b64 s[12:13], 0x4000
	v_lshl_add_u64 v[132:133], s[54:55], 0, v[4:5]
	v_add_co_u32_e32 v132, vcc, 0x18000000, v132
	s_nop 1
	v_addc_co_u32_e32 v133, vcc, 0, v133, vcc
	v_lshl_add_u64 v[134:135], s[54:55], 0, v[2:3]
	v_add_co_u32_e32 v134, vcc, 0x1d00000, v134
	s_nop 1
	v_addc_co_u32_e32 v135, vcc, 0, v135, vcc
	v_add_co_u32_e32 v136, vcc, 0xfffc4000, v6
	s_nop 1
	v_addc_co_u32_e32 v137, vcc, -1, v7, vcc
	global_load_dword v100, v[132:133], off
	v_lshl_add_u64 v[132:133], v[132:133], 0, s[10:11]
	global_load_dword v116, v[134:135], off
	global_load_dword v101, v[132:133], off
	v_lshl_add_u64 v[132:133], v[132:133], 0, s[10:11]
	global_load_dword v117, v[134:135], off offset:256
	global_load_dword v102, v[132:133], off
	v_lshl_add_u64 v[132:133], v[132:133], 0, s[10:11]
	global_load_dword v118, v[134:135], off offset:512
	global_load_dword v103, v[132:133], off
	v_lshl_add_u64 v[132:133], v[132:133], 0, s[10:11]
	global_load_dword v119, v[134:135], off offset:768
	global_load_dword v104, v[132:133], off
	v_lshl_add_u64 v[132:133], v[132:133], 0, s[10:11]
	global_load_dword v120, v[134:135], off offset:1024
	global_load_dword v105, v[132:133], off
	v_lshl_add_u64 v[132:133], v[132:133], 0, s[10:11]
	global_load_dword v121, v[134:135], off offset:1280
	global_load_dword v106, v[132:133], off
	v_lshl_add_u64 v[132:133], v[132:133], 0, s[10:11]
	global_load_dword v122, v[134:135], off offset:1536
	global_load_dword v107, v[132:133], off
	v_lshl_add_u64 v[132:133], v[132:133], 0, s[10:11]
	global_load_dword v123, v[134:135], off offset:1792
	global_load_dword v108, v[132:133], off
	v_lshl_add_u64 v[132:133], v[132:133], 0, s[10:11]
	global_load_dword v124, v[134:135], off offset:2048
	global_load_dword v109, v[132:133], off
	v_lshl_add_u64 v[132:133], v[132:133], 0, s[10:11]
	global_load_dword v125, v[134:135], off offset:2304
	global_load_dword v110, v[132:133], off
	v_lshl_add_u64 v[132:133], v[132:133], 0, s[10:11]
	global_load_dword v126, v[134:135], off offset:2560
	global_load_dword v111, v[132:133], off
	v_lshl_add_u64 v[132:133], v[132:133], 0, s[10:11]
	global_load_dword v127, v[134:135], off offset:2816
	global_load_dword v112, v[132:133], off
	v_lshl_add_u64 v[132:133], v[132:133], 0, s[10:11]
	global_load_dword v128, v[134:135], off offset:3072
	global_load_dword v113, v[132:133], off
	v_lshl_add_u64 v[132:133], v[132:133], 0, s[10:11]
	global_load_dword v129, v[134:135], off offset:3328
	global_load_dword v114, v[132:133], off
	v_lshl_add_u64 v[132:133], v[132:133], 0, s[10:11]
	global_load_dword v130, v[134:135], off offset:3584
	global_load_dword v115, v[132:133], off
	v_lshl_add_u64 v[132:133], v[132:133], 0, s[10:11]
	global_load_dword v131, v[134:135], off offset:3840
	v_lshl_add_u64 v[134:135], v[134:135], 0, s[14:15]
	s_waitcnt vmcnt(0)
.LBB0_423:
	s_add_i32 s6, s6, 16
	s_cmpk_lt_u32 s6, 0x70
	s_waitcnt vmcnt(16)
	v_mov_b32_e32 v20, v100
	v_mov_b32_e32 v36, v116
	v_mov_b32_e32 v21, v101
	v_mov_b32_e32 v37, v117
	v_mov_b32_e32 v22, v102
	v_mov_b32_e32 v38, v118
	v_mov_b32_e32 v23, v103
	v_mov_b32_e32 v39, v119
	v_mov_b32_e32 v24, v104
	v_mov_b32_e32 v40, v120
	v_mov_b32_e32 v25, v105
	v_mov_b32_e32 v41, v121
	v_mov_b32_e32 v26, v106
	v_mov_b32_e32 v42, v122
	v_mov_b32_e32 v27, v107
	v_mov_b32_e32 v43, v123
	v_mov_b32_e32 v28, v108
	v_mov_b32_e32 v44, v124
	v_mov_b32_e32 v29, v109
	v_mov_b32_e32 v45, v125
	v_mov_b32_e32 v30, v110
	v_mov_b32_e32 v46, v126
	v_mov_b32_e32 v31, v111
	v_mov_b32_e32 v47, v127
	v_mov_b32_e32 v32, v112
	v_mov_b32_e32 v48, v128
	v_mov_b32_e32 v33, v113
	v_mov_b32_e32 v49, v129
	v_mov_b32_e32 v34, v114
	v_mov_b32_e32 v50, v130
	v_mov_b32_e32 v35, v115
	v_mov_b32_e32 v51, v131
	s_cbranch_scc0 .Lg2_nopf
	global_load_dword v100, v[132:133], off
	v_lshl_add_u64 v[132:133], v[132:133], 0, s[10:11]
	global_load_dword v116, v[134:135], off
	global_load_dword v101, v[132:133], off
	v_lshl_add_u64 v[132:133], v[132:133], 0, s[10:11]
	global_load_dword v117, v[134:135], off offset:256
	global_load_dword v102, v[132:133], off
	v_lshl_add_u64 v[132:133], v[132:133], 0, s[10:11]
	global_load_dword v118, v[134:135], off offset:512
	global_load_dword v103, v[132:133], off
	v_lshl_add_u64 v[132:133], v[132:133], 0, s[10:11]
	global_load_dword v119, v[134:135], off offset:768
	global_load_dword v104, v[132:133], off
	v_lshl_add_u64 v[132:133], v[132:133], 0, s[10:11]
	global_load_dword v120, v[134:135], off offset:1024
	global_load_dword v105, v[132:133], off
	v_lshl_add_u64 v[132:133], v[132:133], 0, s[10:11]
	global_load_dword v121, v[134:135], off offset:1280
	global_load_dword v106, v[132:133], off
	v_lshl_add_u64 v[132:133], v[132:133], 0, s[10:11]
	global_load_dword v122, v[134:135], off offset:1536
	global_load_dword v107, v[132:133], off
	v_lshl_add_u64 v[132:133], v[132:133], 0, s[10:11]
	global_load_dword v123, v[134:135], off offset:1792
	global_load_dword v108, v[132:133], off
	v_lshl_add_u64 v[132:133], v[132:133], 0, s[10:11]
	global_load_dword v124, v[134:135], off offset:2048
	global_load_dword v109, v[132:133], off
	v_lshl_add_u64 v[132:133], v[132:133], 0, s[10:11]
	global_load_dword v125, v[134:135], off offset:2304
	global_load_dword v110, v[132:133], off
	v_lshl_add_u64 v[132:133], v[132:133], 0, s[10:11]
	global_load_dword v126, v[134:135], off offset:2560
	global_load_dword v111, v[132:133], off
	v_lshl_add_u64 v[132:133], v[132:133], 0, s[10:11]
	global_load_dword v127, v[134:135], off offset:2816
	global_load_dword v112, v[132:133], off
	v_lshl_add_u64 v[132:133], v[132:133], 0, s[10:11]
	global_load_dword v128, v[134:135], off offset:3072
	global_load_dword v113, v[132:133], off
	v_lshl_add_u64 v[132:133], v[132:133], 0, s[10:11]
	global_load_dword v129, v[134:135], off offset:3328
	global_load_dword v114, v[132:133], off
	v_lshl_add_u64 v[132:133], v[132:133], 0, s[10:11]
	global_load_dword v130, v[134:135], off offset:3584
	global_load_dword v115, v[132:133], off
	v_lshl_add_u64 v[132:133], v[132:133], 0, s[10:11]
	global_load_dword v131, v[134:135], off offset:3840
	v_lshl_add_u64 v[134:135], v[134:135], 0, s[14:15]
; __device__ __forceinline__ bf16_t f2bf(float f) { unsigned u = __float_as_uint(f); return (bf16_t)((u + 0x7fffu + ((u >> 16) & 1u)) >> 16); }
; __device__ __forceinline__ void gla_g2_phase(const float* UPD, bf16_t* SP, const float* DEC, int G, int tid) {
;     for (int g = blockIdx.x * 512 + tid; g < 16 * 8192; g += G * 512) {
;     ...
;         for (int n0 = 0; n0 < 128; n0 += 16) { float uu[16], dd[16];
; #pragma unroll
;             for (int x = 0; x < 16; ++x) { uu[x] = p[(size_t)(n0 + x) * 8192]; dd[x] = dc[(n0 + x) * 64]; }
; #pragma unroll
;             for (int x = 0; x < 16; ++x) { po[(size_t)(n0 + x) * 8192] = f2bf(S); S = dd[x] * S + uu[x]; } }
.Lg2_nopf:
	v_bfe_u32 v138, v16, 16, 1
	v_add3_u32 v138, v16, v138, s67
	global_store_short_d16_hi v[136:137], v138, off
	v_lshl_add_u64 v[136:137], v[136:137], 0, s[12:13]
	v_fmac_f32_e32 v20, v16, v36
	v_mov_b32_e32 v16, v20
	v_bfe_u32 v138, v16, 16, 1
	v_add3_u32 v138, v16, v138, s67
	global_store_short_d16_hi v[136:137], v138, off
	v_lshl_add_u64 v[136:137], v[136:137], 0, s[12:13]
	v_fmac_f32_e32 v21, v16, v37
	v_mov_b32_e32 v16, v21
	v_bfe_u32 v138, v16, 16, 1
	v_add3_u32 v138, v16, v138, s67
	global_store_short_d16_hi v[136:137], v138, off
	v_lshl_add_u64 v[136:137], v[136:137], 0, s[12:13]
	v_fmac_f32_e32 v22, v16, v38
	v_mov_b32_e32 v16, v22
	v_bfe_u32 v138, v16, 16, 1
	v_add3_u32 v138, v16, v138, s67
	global_store_short_d16_hi v[136:137], v138, off
	v_lshl_add_u64 v[136:137], v[136:137], 0, s[12:13]
	v_fmac_f32_e32 v23, v16, v39
	v_mov_b32_e32 v16, v23
	v_bfe_u32 v138, v16, 16, 1
	v_add3_u32 v138, v16, v138, s67
	global_store_short_d16_hi v[136:137], v138, off
	v_lshl_add_u64 v[136:137], v[136:137], 0, s[12:13]
	v_fmac_f32_e32 v24, v16, v40
	v_mov_b32_e32 v16, v24
	v_bfe_u32 v138, v16, 16, 1
	v_add3_u32 v138, v16, v138, s67
	global_store_short_d16_hi v[136:137], v138, off
	v_lshl_add_u64 v[136:137], v[136:137], 0, s[12:13]
	v_fmac_f32_e32 v25, v16, v41
	v_mov_b32_e32 v16, v25
	v_bfe_u32 v138, v16, 16, 1
	v_add3_u32 v138, v16, v138, s67
	global_store_short_d16_hi v[136:137], v138, off
	v_lshl_add_u64 v[136:137], v[136:137], 0, s[12:13]
	v_fmac_f32_e32 v26, v16, v42
	v_mov_b32_e32 v16, v26
	v_bfe_u32 v138, v16, 16, 1
	v_add3_u32 v138, v16, v138, s67
	global_store_short_d16_hi v[136:137], v138, off
	v_lshl_add_u64 v[136:137], v[136:137], 0, s[12:13]
	v_fmac_f32_e32 v27, v16, v43
	v_mov_b32_e32 v16, v27
	v_bfe_u32 v138, v16, 16, 1
	v_add3_u32 v138, v16, v138, s67
	global_store_short_d16_hi v[136:137], v138, off
	v_lshl_add_u64 v[136:137], v[136:137], 0, s[12:13]
	v_fmac_f32_e32 v28, v16, v44
	v_mov_b32_e32 v16, v28
	v_bfe_u32 v138, v16, 16, 1
	v_add3_u32 v138, v16, v138, s67
	global_store_short_d16_hi v[136:137], v138, off
	v_lshl_add_u64 v[136:137], v[136:137], 0, s[12:13]
	v_fmac_f32_e32 v29, v16, v45
	v_mov_b32_e32 v16, v29
	v_bfe_u32 v138, v16, 16, 1
	v_add3_u32 v138, v16, v138, s67
	global_store_short_d16_hi v[136:137], v138, off
	v_lshl_add_u64 v[136:137], v[136:137], 0, s[12:13]
	v_fmac_f32_e32 v30, v16, v46
	v_mov_b32_e32 v16, v30
	v_bfe_u32 v138, v16, 16, 1
	v_add3_u32 v138, v16, v138, s67
	global_store_short_d16_hi v[136:137], v138, off
	v_lshl_add_u64 v[136:137], v[136:137], 0, s[12:13]
	v_fmac_f32_e32 v31, v16, v47
	v_mov_b32_e32 v16, v31
	v_bfe_u32 v138, v16, 16, 1
	v_add3_u32 v138, v16, v138, s67
	global_store_short_d16_hi v[136:137], v138, off
	v_lshl_add_u64 v[136:137], v[136:137], 0, s[12:13]
	v_fmac_f32_e32 v32, v16, v48
	v_mov_b32_e32 v16, v32
	v_bfe_u32 v138, v16, 16, 1
	v_add3_u32 v138, v16, v138, s67
	global_store_short_d16_hi v[136:137], v138, off
	v_lshl_add_u64 v[136:137], v[136:137], 0, s[12:13]
	v_fmac_f32_e32 v33, v16, v49
	v_mov_b32_e32 v16, v33
	v_bfe_u32 v138, v16, 16, 1
	v_add3_u32 v138, v16, v138, s67
	global_store_short_d16_hi v[136:137], v138, off
	v_lshl_add_u64 v[136:137], v[136:137], 0, s[12:13]
	v_fmac_f32_e32 v34, v16, v50
	v_mov_b32_e32 v16, v34
	v_bfe_u32 v138, v16, 16, 1
	v_add3_u32 v138, v16, v138, s67
	global_store_short_d16_hi v[136:137], v138, off
	v_lshl_add_u64 v[136:137], v[136:137], 0, s[12:13]
	v_fmac_f32_e32 v35, v16, v51
	v_mov_b32_e32 v16, v35
	s_cbranch_scc1 .LBB0_423
	v_add_u32_e32 v1, s56, v1
	s_mov_b32 s6, 0x1ffff
	v_cmp_lt_i32_e32 vcc, s6, v1
	s_or_b64 s[8:9], vcc, s[8:9]
	v_add_u16_e32 v8, s56, v8
	s_andn2_b64 exec, exec, s[8:9]
	s_cbranch_execnz .LBB0_422

; __device__ __forceinline__ void conv_phase(LAS unsigned char* lds, const bf16_t* PROJ, const float* cw, const float* cb, const float* lg, const float* lb, bf16_t* MIXIN, int G, int tid) {
;     ...
;         float y[32];
; #pragma unroll
;         for (int blk = 0; blk < 4; ++blk) { float win[38];
; #pragma unroll
;             for (int x = 0; x < 38; ++x) win[x] = U[(8 * blk + x) * 512 + c];
; #pragma unroll
;             for (int o = 0; o < 8; ++o) { float acc = bias;
; #pragma unroll
;                 for (int k = 0; k < 31; ++k) acc += w[k] * win[o + k];
;                 y[8 * blk + o] = acc; } }
.LBB0_433:
	v_lshl_add_u32 v62, v8, 2, 0
	v_add_u32_e32 v63, 0x10000, v62
	v_add_u32_e32 v74, 0x13800, v62
	v_add_u32_e32 v81, 0x17000, v62
	v_add_u32_e32 v88, 0x1a800, v62
	v_add_u32_e32 v95, 0x1e000, v62
	v_lshlrev_b32_e32 v61, 3, v12
	s_waitcnt lgkmcnt(0)
	s_barrier
	ds_read2st64_b32 v[70:71], v62 offset1:8
	ds_read2st64_b32 v[72:73], v62 offset0:16 offset1:24
	ds_read2st64_b32 v[28:29], v62 offset0:32 offset1:40
	ds_read2st64_b32 v[26:27], v62 offset0:48 offset1:56
	ds_read2st64_b32 v[24:25], v62 offset0:64 offset1:72
	ds_read2st64_b32 v[22:23], v62 offset0:80 offset1:88
	ds_read2st64_b32 v[20:21], v62 offset0:96 offset1:104
	ds_read2st64_b32 v[18:19], v62 offset0:112 offset1:120
	ds_read2st64_b32 v[16:17], v62 offset0:128 offset1:136
	ds_read2st64_b32 v[14:15], v62 offset0:144 offset1:152
	ds_read2st64_b32 v[12:13], v62 offset0:160 offset1:168
	ds_read2st64_b32 v[10:11], v62 offset0:176 offset1:184
	ds_read2st64_b32 v[6:7], v62 offset0:192 offset1:200
	ds_read2st64_b32 v[4:5], v62 offset0:208 offset1:216
	ds_read2st64_b32 v[2:3], v62 offset0:224 offset1:232
	ds_read2st64_b32 v[0:1], v62 offset0:240 offset1:248
	ds_read_b32 v64, v63
	ds_read_b32 v74, v74
	ds_read_b32 v81, v81
	ds_read_b32 v88, v88
	ds_read_b32 v95, v95
	v_add_u32_e32 v63, 0x10800, v62
	v_add_u32_e32 v75, 0x14000, v62
	v_add_u32_e32 v82, 0x17800, v62
	v_add_u32_e32 v89, 0x1b000, v62
	v_add_u32_e32 v96, 0x1e800, v62
	ds_read_b32 v65, v63
	ds_read_b32 v75, v75
	ds_read_b32 v82, v82
	ds_read_b32 v89, v89
	ds_read_b32 v96, v96
	v_add_u32_e32 v63, 0x11000, v62
	v_add_u32_e32 v76, 0x14800, v62
	v_add_u32_e32 v83, 0x18000, v62
	v_add_u32_e32 v90, 0x1b800, v62
	ds_read_b32 v66, v63
	ds_read_b32 v76, v76
	ds_read_b32 v83, v83
	ds_read_b32 v90, v90
	v_add_u32_e32 v63, 0x11800, v62
	v_add_u32_e32 v77, 0x15000, v62
	v_add_u32_e32 v84, 0x18800, v62
	v_add_u32_e32 v91, 0x1c000, v62
	ds_read_b32 v67, v63
	ds_read_b32 v77, v77
	ds_read_b32 v84, v84
	ds_read_b32 v91, v91
	v_add_u32_e32 v63, 0x12000, v62
	v_add_u32_e32 v78, 0x15800, v62
	v_add_u32_e32 v85, 0x19000, v62
	v_add_u32_e32 v92, 0x1c800, v62
	ds_read_b32 v68, v63
	ds_read_b32 v78, v78
	ds_read_b32 v85, v85
	ds_read_b32 v92, v92
	v_add_u32_e32 v63, 0x12800, v62
	v_add_u32_e32 v79, 0x16000, v62
	v_add_u32_e32 v86, 0x19800, v62
	v_add_u32_e32 v93, 0x1d000, v62
	ds_read_b32 v69, v63
	ds_read_b32 v79, v79
	ds_read_b32 v86, v86
	ds_read_b32 v93, v93
	s_waitcnt vmcnt(0) lgkmcnt(14)
	v_fma_f32 v63, v36, v70, v49
	v_fmac_f32_e32 v63, v35, v71
	v_fma_f32 v70, v36, v71, v49
	v_fmac_f32_e32 v63, v34, v72
	v_fmac_f32_e32 v70, v35, v72
	v_fma_f32 v71, v36, v72, v49
	v_fmac_f32_e32 v63, v33, v73
	v_fmac_f32_e32 v70, v34, v73
	v_fmac_f32_e32 v71, v35, v73
	v_fma_f32 v72, v36, v73, v49
	v_fmac_f32_e32 v63, v31, v28
	v_fmac_f32_e32 v70, v33, v28
	v_fmac_f32_e32 v71, v34, v28
	v_fmac_f32_e32 v72, v35, v28
	v_fma_f32 v28, v36, v28, v49
	v_fmac_f32_e32 v63, v9, v29
	v_fmac_f32_e32 v70, v31, v29
	v_fmac_f32_e32 v71, v33, v29
	v_fmac_f32_e32 v72, v34, v29
	v_fmac_f32_e32 v28, v35, v29
	v_fma_f32 v29, v36, v29, v49
	v_fmac_f32_e32 v63, v32, v26
	v_fmac_f32_e32 v70, v9, v26
	v_fmac_f32_e32 v71, v31, v26
	v_fmac_f32_e32 v72, v33, v26
	v_fmac_f32_e32 v28, v34, v26
	v_fmac_f32_e32 v29, v35, v26
	v_fma_f32 v26, v36, v26, v49
	v_fmac_f32_e32 v63, v30, v27
	v_fmac_f32_e32 v70, v32, v27
	v_fmac_f32_e32 v71, v9, v27
	v_fmac_f32_e32 v72, v31, v27
	v_fmac_f32_e32 v28, v33, v27
	v_fmac_f32_e32 v29, v34, v27
	v_fmac_f32_e32 v26, v35, v27
	v_fma_f32 v27, v36, v27, v49
	v_fmac_f32_e32 v63, v44, v24
	v_fmac_f32_e32 v70, v30, v24
	v_fmac_f32_e32 v71, v32, v24
	v_fmac_f32_e32 v72, v9, v24
	v_fmac_f32_e32 v28, v31, v24
	v_fmac_f32_e32 v29, v33, v24
	v_fmac_f32_e32 v26, v34, v24
	v_fmac_f32_e32 v27, v35, v24
	v_fma_f32 v24, v36, v24, v49
	v_fmac_f32_e32 v63, v43, v25
	v_fmac_f32_e32 v70, v44, v25
	v_fmac_f32_e32 v71, v30, v25
	v_fmac_f32_e32 v72, v32, v25
	v_fmac_f32_e32 v28, v9, v25
	v_fmac_f32_e32 v29, v31, v25
	v_fmac_f32_e32 v26, v33, v25
	v_fmac_f32_e32 v27, v34, v25
	v_fmac_f32_e32 v24, v35, v25
	v_fma_f32 v25, v36, v25, v49
	v_fmac_f32_e32 v63, v42, v22
	v_fmac_f32_e32 v70, v43, v22
	v_fmac_f32_e32 v71, v44, v22
	v_fmac_f32_e32 v72, v30, v22
	v_fmac_f32_e32 v28, v32, v22
	v_fmac_f32_e32 v29, v9, v22
	v_fmac_f32_e32 v26, v31, v22
	v_fmac_f32_e32 v27, v33, v22
	v_fmac_f32_e32 v24, v34, v22
	v_fmac_f32_e32 v25, v35, v22
	v_fma_f32 v22, v36, v22, v49
	v_fmac_f32_e32 v63, v41, v23
	v_fmac_f32_e32 v70, v42, v23
	v_fmac_f32_e32 v71, v43, v23
	v_fmac_f32_e32 v72, v44, v23
	v_fmac_f32_e32 v28, v30, v23
	v_fmac_f32_e32 v29, v32, v23
	v_fmac_f32_e32 v26, v9, v23
	v_fmac_f32_e32 v27, v31, v23
	v_fmac_f32_e32 v24, v33, v23
	v_fmac_f32_e32 v25, v34, v23
	v_fmac_f32_e32 v22, v35, v23
	v_fma_f32 v23, v36, v23, v49
	v_fmac_f32_e32 v63, v39, v20
	v_fmac_f32_e32 v70, v41, v20
	v_fmac_f32_e32 v71, v42, v20
	v_fmac_f32_e32 v72, v43, v20
	v_fmac_f32_e32 v28, v44, v20
	v_fmac_f32_e32 v29, v30, v20
	v_fmac_f32_e32 v26, v32, v20
	v_fmac_f32_e32 v27, v9, v20
	v_fmac_f32_e32 v24, v31, v20
	v_fmac_f32_e32 v25, v33, v20
	v_fmac_f32_e32 v22, v34, v20
	v_fmac_f32_e32 v23, v35, v20
	v_fma_f32 v20, v36, v20, v49
	v_fmac_f32_e32 v63, v37, v21
	v_fmac_f32_e32 v70, v39, v21
	v_fmac_f32_e32 v71, v41, v21
	v_fmac_f32_e32 v72, v42, v21
	v_fmac_f32_e32 v28, v43, v21
	v_fmac_f32_e32 v29, v44, v21
	v_fmac_f32_e32 v26, v30, v21
	v_fmac_f32_e32 v27, v32, v21
	v_fmac_f32_e32 v24, v9, v21
	v_fmac_f32_e32 v25, v31, v21
	v_fmac_f32_e32 v22, v33, v21
	v_fmac_f32_e32 v23, v34, v21
	v_fmac_f32_e32 v20, v35, v21
	v_fma_f32 v21, v36, v21, v49
	v_fmac_f32_e32 v63, v40, v18
	v_fmac_f32_e32 v70, v37, v18
; __device__ __forceinline__ void conv_phase(LAS unsigned char* lds, const bf16_t* PROJ, const float* cw, const float* cb, const float* lg, const float* lb, bf16_t* MIXIN, int G, int tid) {
;     ...
;         for (int blk = 0; blk < 4; ++blk) { float win[38];
; #pragma unroll
;             for (int x = 0; x < 38; ++x) win[x] = U[(8 * blk + x) * 512 + c];
; #pragma unroll
;             for (int o = 0; o < 8; ++o) { float acc = bias;
; #pragma unroll
;                 for (int k = 0; k < 31; ++k) acc += w[k] * win[o + k];
;                 y[8 * blk + o] = acc; } }
	v_fmac_f32_e32 v71, v39, v18
	v_fmac_f32_e32 v72, v41, v18
	v_fmac_f32_e32 v28, v42, v18
	v_fmac_f32_e32 v29, v43, v18
	v_fmac_f32_e32 v26, v44, v18
	v_fmac_f32_e32 v27, v30, v18
	v_fmac_f32_e32 v24, v32, v18
	v_fmac_f32_e32 v25, v9, v18
	v_fmac_f32_e32 v22, v31, v18
	v_fmac_f32_e32 v23, v33, v18
	v_fmac_f32_e32 v20, v34, v18
	v_fmac_f32_e32 v21, v35, v18
	v_fma_f32 v18, v36, v18, v49
	v_fmac_f32_e32 v63, v38, v19
	v_fmac_f32_e32 v70, v40, v19
	v_fmac_f32_e32 v71, v37, v19
	v_fmac_f32_e32 v72, v39, v19
	v_fmac_f32_e32 v28, v41, v19
	v_fmac_f32_e32 v29, v42, v19
	v_fmac_f32_e32 v26, v43, v19
	v_fmac_f32_e32 v27, v44, v19
	v_fmac_f32_e32 v24, v30, v19
	v_fmac_f32_e32 v25, v32, v19
	v_fmac_f32_e32 v22, v9, v19
	v_fmac_f32_e32 v23, v31, v19
	v_fmac_f32_e32 v20, v33, v19
	v_fmac_f32_e32 v21, v34, v19
	v_fmac_f32_e32 v18, v35, v19
	v_fma_f32 v19, v36, v19, v49
	v_fmac_f32_e32 v63, v53, v16
	v_fmac_f32_e32 v70, v38, v16
	v_fmac_f32_e32 v71, v40, v16
	v_fmac_f32_e32 v72, v37, v16
	v_fmac_f32_e32 v28, v39, v16
	v_fmac_f32_e32 v29, v41, v16
	v_fmac_f32_e32 v26, v42, v16
	v_fmac_f32_e32 v27, v43, v16
	v_fmac_f32_e32 v24, v44, v16
	v_fmac_f32_e32 v25, v30, v16
	v_fmac_f32_e32 v22, v32, v16
	v_fmac_f32_e32 v23, v9, v16
	v_fmac_f32_e32 v20, v31, v16
	v_fmac_f32_e32 v21, v33, v16
	v_fmac_f32_e32 v18, v34, v16
	v_fmac_f32_e32 v19, v35, v16
	v_fma_f32 v16, v36, v16, v49
	v_fmac_f32_e32 v63, v60, v17
	v_fmac_f32_e32 v70, v53, v17
	v_fmac_f32_e32 v71, v38, v17
	v_fmac_f32_e32 v72, v40, v17
	v_fmac_f32_e32 v28, v37, v17
	v_fmac_f32_e32 v29, v39, v17
	v_fmac_f32_e32 v26, v41, v17
	v_fmac_f32_e32 v27, v42, v17
	v_fmac_f32_e32 v24, v43, v17
	v_fmac_f32_e32 v25, v44, v17
	v_fmac_f32_e32 v22, v30, v17
	v_fmac_f32_e32 v23, v32, v17
	v_fmac_f32_e32 v20, v9, v17
	v_fmac_f32_e32 v21, v31, v17
	v_fmac_f32_e32 v18, v33, v17
	v_fmac_f32_e32 v19, v34, v17
	v_fmac_f32_e32 v16, v35, v17
	v_fma_f32 v17, v36, v17, v49
	v_fmac_f32_e32 v63, v52, v14
	v_fmac_f32_e32 v70, v60, v14
	v_fmac_f32_e32 v71, v53, v14
	v_fmac_f32_e32 v72, v38, v14
	v_fmac_f32_e32 v28, v40, v14
	v_fmac_f32_e32 v29, v37, v14
	v_fmac_f32_e32 v26, v39, v14
	v_fmac_f32_e32 v27, v41, v14
	v_fmac_f32_e32 v24, v42, v14
	v_fmac_f32_e32 v25, v43, v14
	v_fmac_f32_e32 v22, v44, v14
	v_fmac_f32_e32 v23, v30, v14
	v_fmac_f32_e32 v20, v32, v14
	v_fmac_f32_e32 v21, v9, v14
	v_fmac_f32_e32 v18, v31, v14
	v_fmac_f32_e32 v19, v33, v14
	v_fmac_f32_e32 v16, v34, v14
	v_fmac_f32_e32 v17, v35, v14
	v_fma_f32 v14, v36, v14, v49
	v_fmac_f32_e32 v63, v51, v15
	v_fmac_f32_e32 v70, v52, v15
	v_fmac_f32_e32 v71, v60, v15
	v_fmac_f32_e32 v72, v53, v15
	v_fmac_f32_e32 v28, v38, v15
	v_fmac_f32_e32 v29, v40, v15
	v_fmac_f32_e32 v26, v37, v15
	v_fmac_f32_e32 v27, v39, v15
	v_fmac_f32_e32 v24, v41, v15
	v_fmac_f32_e32 v25, v42, v15
	v_fmac_f32_e32 v22, v43, v15
	v_fmac_f32_e32 v23, v44, v15
	v_fmac_f32_e32 v20, v30, v15
	v_fmac_f32_e32 v21, v32, v15
	v_fmac_f32_e32 v18, v9, v15
	v_fmac_f32_e32 v19, v31, v15
	v_fmac_f32_e32 v16, v33, v15
	v_fmac_f32_e32 v17, v34, v15
	v_fmac_f32_e32 v14, v35, v15
	v_fma_f32 v15, v36, v15, v49
	v_fmac_f32_e32 v63, v50, v12
	v_fmac_f32_e32 v70, v51, v12
	v_fmac_f32_e32 v71, v52, v12
	v_fmac_f32_e32 v72, v60, v12
	v_fmac_f32_e32 v28, v53, v12
	v_fmac_f32_e32 v29, v38, v12
	v_fmac_f32_e32 v26, v40, v12
	v_fmac_f32_e32 v27, v37, v12
	v_fmac_f32_e32 v24, v39, v12
	v_fmac_f32_e32 v25, v41, v12
	v_fmac_f32_e32 v22, v42, v12
	v_fmac_f32_e32 v23, v43, v12
	v_fmac_f32_e32 v20, v44, v12
	v_fmac_f32_e32 v21, v30, v12
	v_fmac_f32_e32 v18, v32, v12
	v_fmac_f32_e32 v19, v9, v12
	v_fmac_f32_e32 v16, v31, v12
	v_fmac_f32_e32 v17, v33, v12
	v_fmac_f32_e32 v14, v34, v12
	v_fmac_f32_e32 v15, v35, v12
	v_fma_f32 v12, v36, v12, v49
	v_fmac_f32_e32 v63, v59, v13
	v_fmac_f32_e32 v70, v50, v13
	v_fmac_f32_e32 v71, v51, v13
	v_fmac_f32_e32 v72, v52, v13
	v_fmac_f32_e32 v28, v60, v13
	v_fmac_f32_e32 v29, v53, v13
	v_fmac_f32_e32 v26, v38, v13
	v_fmac_f32_e32 v27, v40, v13
	v_fmac_f32_e32 v24, v37, v13
	v_fmac_f32_e32 v25, v39, v13
	v_fmac_f32_e32 v22, v41, v13
	v_fmac_f32_e32 v23, v42, v13
	v_fmac_f32_e32 v20, v43, v13
	v_fmac_f32_e32 v21, v44, v13
	v_fmac_f32_e32 v18, v30, v13
	v_fmac_f32_e32 v19, v32, v13
	v_fmac_f32_e32 v16, v9, v13
	v_fmac_f32_e32 v17, v31, v13
	v_fmac_f32_e32 v14, v33, v13
	v_fmac_f32_e32 v15, v34, v13
	v_fmac_f32_e32 v12, v35, v13
	v_fma_f32 v13, v36, v13, v49
	v_fmac_f32_e32 v63, v47, v10
	v_fmac_f32_e32 v70, v59, v10
	v_fmac_f32_e32 v71, v50, v10
	v_fmac_f32_e32 v72, v51, v10
	v_fmac_f32_e32 v28, v52, v10
	v_fmac_f32_e32 v29, v60, v10
	v_fmac_f32_e32 v26, v53, v10
	v_fmac_f32_e32 v27, v38, v10
	v_fmac_f32_e32 v24, v40, v10
	v_fmac_f32_e32 v25, v37, v10
	v_fmac_f32_e32 v22, v39, v10
	v_fmac_f32_e32 v23, v41, v10
	v_fmac_f32_e32 v20, v42, v10
	v_fmac_f32_e32 v21, v43, v10
	v_fmac_f32_e32 v18, v44, v10
	v_fmac_f32_e32 v19, v30, v10
	v_fmac_f32_e32 v16, v32, v10
	v_fmac_f32_e32 v17, v9, v10
	v_fmac_f32_e32 v14, v31, v10
	v_fmac_f32_e32 v15, v33, v10
	v_fmac_f32_e32 v12, v34, v10
	v_fmac_f32_e32 v13, v35, v10
	v_fma_f32 v10, v36, v10, v49
	v_fmac_f32_e32 v63, v46, v11
	v_fmac_f32_e32 v70, v47, v11
	v_fmac_f32_e32 v71, v59, v11
	v_fmac_f32_e32 v72, v50, v11
	v_fmac_f32_e32 v28, v51, v11
	v_fmac_f32_e32 v29, v52, v11
	v_fmac_f32_e32 v26, v60, v11
	v_fmac_f32_e32 v27, v53, v11
	v_fmac_f32_e32 v24, v38, v11
	v_fmac_f32_e32 v25, v40, v11
	v_fmac_f32_e32 v22, v37, v11
	v_fmac_f32_e32 v23, v39, v11
	v_fmac_f32_e32 v20, v41, v11
	v_fmac_f32_e32 v21, v42, v11
	v_fmac_f32_e32 v18, v43, v11
	v_fmac_f32_e32 v19, v44, v11
	v_fmac_f32_e32 v16, v30, v11
	v_fmac_f32_e32 v17, v32, v11
	v_fmac_f32_e32 v14, v9, v11
; __device__ __forceinline__ void conv_phase(LAS unsigned char* lds, const bf16_t* PROJ, const float* cw, const float* cb, const float* lg, const float* lb, bf16_t* MIXIN, int G, int tid) {
;     ...
;         for (int blk = 0; blk < 4; ++blk) { float win[38];
; #pragma unroll
;             for (int x = 0; x < 38; ++x) win[x] = U[(8 * blk + x) * 512 + c];
; #pragma unroll
;             for (int o = 0; o < 8; ++o) { float acc = bias;
; #pragma unroll
;                 for (int k = 0; k < 31; ++k) acc += w[k] * win[o + k];
;                 y[8 * blk + o] = acc; } }
	v_fmac_f32_e32 v15, v31, v11
	v_fmac_f32_e32 v12, v33, v11
	v_fmac_f32_e32 v13, v34, v11
	v_fmac_f32_e32 v10, v35, v11
	v_fma_f32 v11, v36, v11, v49
	v_fmac_f32_e32 v63, v48, v6
	v_fmac_f32_e32 v70, v46, v6
	v_fmac_f32_e32 v71, v47, v6
	v_fmac_f32_e32 v72, v59, v6
	v_fmac_f32_e32 v28, v50, v6
	v_fmac_f32_e32 v29, v51, v6
	v_fmac_f32_e32 v26, v52, v6
	v_fmac_f32_e32 v27, v60, v6
	v_fmac_f32_e32 v24, v53, v6
	v_fmac_f32_e32 v25, v38, v6
	v_fmac_f32_e32 v22, v40, v6
	v_fmac_f32_e32 v23, v37, v6
	v_fmac_f32_e32 v20, v39, v6
	v_fmac_f32_e32 v21, v41, v6
	v_fmac_f32_e32 v18, v42, v6
	v_fmac_f32_e32 v19, v43, v6
	v_fmac_f32_e32 v16, v44, v6
	v_fmac_f32_e32 v17, v30, v6
	v_fmac_f32_e32 v14, v32, v6
	v_fmac_f32_e32 v15, v9, v6
	v_fmac_f32_e32 v12, v31, v6
	v_fmac_f32_e32 v13, v33, v6
	v_fmac_f32_e32 v10, v34, v6
	v_fmac_f32_e32 v11, v35, v6
	v_fma_f32 v6, v36, v6, v49
	v_fmac_f32_e32 v63, v56, v7
	v_fmac_f32_e32 v70, v48, v7
	v_fmac_f32_e32 v71, v46, v7
	v_fmac_f32_e32 v72, v47, v7
	v_fmac_f32_e32 v28, v59, v7
	v_fmac_f32_e32 v29, v50, v7
	v_fmac_f32_e32 v26, v51, v7
	v_fmac_f32_e32 v27, v52, v7
	v_fmac_f32_e32 v24, v60, v7
	v_fmac_f32_e32 v25, v53, v7
	v_fmac_f32_e32 v22, v38, v7
	v_fmac_f32_e32 v23, v40, v7
	v_fmac_f32_e32 v20, v37, v7
	v_fmac_f32_e32 v21, v39, v7
	v_fmac_f32_e32 v18, v41, v7
	v_fmac_f32_e32 v19, v42, v7
	v_fmac_f32_e32 v16, v43, v7
	v_fmac_f32_e32 v17, v44, v7
	v_fmac_f32_e32 v14, v30, v7
	v_fmac_f32_e32 v15, v32, v7
	v_fmac_f32_e32 v12, v9, v7
	v_fmac_f32_e32 v13, v31, v7
	v_fmac_f32_e32 v10, v33, v7
	v_fmac_f32_e32 v11, v34, v7
	v_fmac_f32_e32 v6, v35, v7
	v_fma_f32 v7, v36, v7, v49
	v_fmac_f32_e32 v63, v45, v4
	v_fmac_f32_e32 v70, v56, v4
	v_fmac_f32_e32 v71, v48, v4
	v_fmac_f32_e32 v72, v46, v4
	v_fmac_f32_e32 v28, v47, v4
	v_fmac_f32_e32 v29, v59, v4
	v_fmac_f32_e32 v26, v50, v4
	v_fmac_f32_e32 v27, v51, v4
	v_fmac_f32_e32 v24, v52, v4
	v_fmac_f32_e32 v25, v60, v4
	v_fmac_f32_e32 v22, v53, v4
	v_fmac_f32_e32 v23, v38, v4
	v_fmac_f32_e32 v20, v40, v4
	v_fmac_f32_e32 v21, v37, v4
	v_fmac_f32_e32 v18, v39, v4
	v_fmac_f32_e32 v19, v41, v4
	v_fmac_f32_e32 v16, v42, v4
	v_fmac_f32_e32 v17, v43, v4
	v_fmac_f32_e32 v14, v44, v4
	v_fmac_f32_e32 v15, v30, v4
	v_fmac_f32_e32 v12, v32, v4
	v_fmac_f32_e32 v13, v9, v4
	v_fmac_f32_e32 v10, v31, v4
	v_fmac_f32_e32 v11, v33, v4
	v_fmac_f32_e32 v6, v34, v4
	v_fmac_f32_e32 v7, v35, v4
	v_fma_f32 v4, v36, v4, v49
	v_fmac_f32_e32 v63, v58, v5
	v_fmac_f32_e32 v70, v45, v5
	v_fmac_f32_e32 v71, v56, v5
	v_fmac_f32_e32 v72, v48, v5
	v_fmac_f32_e32 v28, v46, v5
	v_fmac_f32_e32 v29, v47, v5
	v_fmac_f32_e32 v26, v59, v5
	v_fmac_f32_e32 v27, v50, v5
	v_fmac_f32_e32 v24, v51, v5
	v_fmac_f32_e32 v25, v52, v5
	v_fmac_f32_e32 v22, v60, v5
	v_fmac_f32_e32 v23, v53, v5
	v_fmac_f32_e32 v20, v38, v5
	v_fmac_f32_e32 v21, v40, v5
	v_fmac_f32_e32 v18, v37, v5
	v_fmac_f32_e32 v19, v39, v5
	v_fmac_f32_e32 v16, v41, v5
	v_fmac_f32_e32 v17, v42, v5
	v_fmac_f32_e32 v14, v43, v5
	v_fmac_f32_e32 v15, v44, v5
	v_fmac_f32_e32 v12, v30, v5
	v_fmac_f32_e32 v13, v32, v5
	v_fmac_f32_e32 v10, v9, v5
	v_fmac_f32_e32 v11, v31, v5
	v_fmac_f32_e32 v6, v33, v5
	v_fmac_f32_e32 v7, v34, v5
	v_fmac_f32_e32 v4, v35, v5
	v_fma_f32 v5, v36, v5, v49
	v_fmac_f32_e32 v63, v57, v2
	v_fmac_f32_e32 v70, v58, v2
	v_fmac_f32_e32 v71, v45, v2
	v_fmac_f32_e32 v72, v56, v2
	v_fmac_f32_e32 v28, v48, v2
	v_fmac_f32_e32 v29, v46, v2
	v_fmac_f32_e32 v26, v47, v2
	v_fmac_f32_e32 v27, v59, v2
	v_fmac_f32_e32 v24, v50, v2
	v_fmac_f32_e32 v25, v51, v2
	v_fmac_f32_e32 v22, v52, v2
	v_fmac_f32_e32 v23, v60, v2
	v_fmac_f32_e32 v20, v53, v2
	v_fmac_f32_e32 v21, v38, v2
	v_fmac_f32_e32 v18, v40, v2
	v_fmac_f32_e32 v19, v37, v2
	v_fmac_f32_e32 v16, v39, v2
	v_fmac_f32_e32 v17, v41, v2
	v_fmac_f32_e32 v14, v42, v2
	v_fmac_f32_e32 v15, v43, v2
	v_fmac_f32_e32 v12, v44, v2
	v_fmac_f32_e32 v13, v30, v2
	v_fmac_f32_e32 v10, v32, v2
	v_fmac_f32_e32 v11, v9, v2
	v_fmac_f32_e32 v6, v31, v2
	v_fmac_f32_e32 v7, v33, v2
	v_fmac_f32_e32 v4, v34, v2
	v_fmac_f32_e32 v5, v35, v2
	v_fma_f32 v2, v36, v2, v49
	v_fmac_f32_e32 v63, v54, v3
	v_fmac_f32_e32 v70, v57, v3
	v_fmac_f32_e32 v71, v58, v3
	v_fmac_f32_e32 v72, v45, v3
	v_fmac_f32_e32 v28, v56, v3
	v_fmac_f32_e32 v29, v48, v3
	v_fmac_f32_e32 v26, v46, v3
	v_fmac_f32_e32 v27, v47, v3
	v_fmac_f32_e32 v24, v59, v3
	v_fmac_f32_e32 v25, v50, v3
	v_fmac_f32_e32 v22, v51, v3
	v_fmac_f32_e32 v23, v52, v3
	v_fmac_f32_e32 v20, v60, v3
	v_fmac_f32_e32 v21, v53, v3
	v_fmac_f32_e32 v18, v38, v3
	v_fmac_f32_e32 v19, v40, v3
	v_fmac_f32_e32 v16, v37, v3
	v_fmac_f32_e32 v17, v39, v3
	v_fmac_f32_e32 v14, v41, v3
	v_fmac_f32_e32 v15, v42, v3
	v_fmac_f32_e32 v12, v43, v3
	v_fmac_f32_e32 v13, v44, v3
	v_fmac_f32_e32 v10, v30, v3
	v_fmac_f32_e32 v11, v32, v3
	v_fmac_f32_e32 v6, v9, v3
	v_fmac_f32_e32 v7, v31, v3
	v_fmac_f32_e32 v4, v33, v3
	v_fmac_f32_e32 v5, v34, v3
	v_fmac_f32_e32 v2, v35, v3
	v_fma_f32 v3, v36, v3, v49
	v_fmac_f32_e32 v63, v55, v0
	v_fmac_f32_e32 v70, v54, v0
	v_fmac_f32_e32 v71, v57, v0
	v_fmac_f32_e32 v72, v58, v0
	v_fmac_f32_e32 v28, v45, v0
	v_fmac_f32_e32 v29, v56, v0
	v_fmac_f32_e32 v26, v48, v0
	v_fmac_f32_e32 v27, v46, v0
	v_fmac_f32_e32 v24, v47, v0
	v_fmac_f32_e32 v25, v59, v0
	v_fmac_f32_e32 v22, v50, v0
	v_fmac_f32_e32 v23, v51, v0
	v_fmac_f32_e32 v20, v52, v0
	v_fmac_f32_e32 v21, v60, v0
	v_fmac_f32_e32 v18, v53, v0
	v_fmac_f32_e32 v19, v38, v0
	v_fmac_f32_e32 v16, v40, v0
	v_fmac_f32_e32 v17, v37, v0
	v_fmac_f32_e32 v14, v39, v0
	v_fmac_f32_e32 v15, v41, v0
	v_fmac_f32_e32 v12, v42, v0
	v_fmac_f32_e32 v13, v43, v0
	v_fmac_f32_e32 v10, v44, v0
	v_fmac_f32_e32 v11, v30, v0
	v_fmac_f32_e32 v6, v32, v0
	v_fmac_f32_e32 v7, v9, v0
	v_fmac_f32_e32 v4, v31, v0
	v_fmac_f32_e32 v5, v33, v0
	v_fmac_f32_e32 v2, v34, v0
	v_fmac_f32_e32 v3, v35, v0
	v_fma_f32 v0, v36, v0, v49
	v_fmac_f32_e32 v0, v35, v1
	v_fmac_f32_e32 v49, v36, v1
	v_add_u32_e32 v73, 0x13000, v62
	v_fmac_f32_e32 v0, v34, v64
	v_fmac_f32_e32 v49, v35, v64
	ds_read_b32 v73, v73
	v_fmac_f32_e32 v3, v34, v1
	v_fmac_f32_e32 v0, v33, v65
	v_fmac_f32_e32 v49, v34, v65
	v_fmac_f32_e32 v2, v33, v1
	v_fmac_f32_e32 v3, v33, v64
	v_fmac_f32_e32 v0, v31, v66
	v_fmac_f32_e32 v49, v33, v66
	v_fmac_f32_e32 v5, v31, v1
	v_fmac_f32_e32 v2, v31, v64
	v_fmac_f32_e32 v3, v31, v65
	s_waitcnt lgkmcnt(12)
; __device__ __forceinline__ void conv_phase(LAS unsigned char* lds, const bf16_t* PROJ, const float* cw, const float* cb, const float* lg, const float* lb, bf16_t* MIXIN, int G, int tid) {
;     ...
;         for (int blk = 0; blk < 4; ++blk) { float win[38];
; #pragma unroll
;             for (int x = 0; x < 38; ++x) win[x] = U[(8 * blk + x) * 512 + c];
; #pragma unroll
;             for (int o = 0; o < 8; ++o) { float acc = bias;
; #pragma unroll
;                 for (int k = 0; k < 31; ++k) acc += w[k] * win[o + k];
;                 y[8 * blk + o] = acc; } }
	v_fmac_f32_e32 v0, v9, v67
	v_fmac_f32_e32 v49, v31, v67
	v_fmac_f32_e32 v4, v9, v1
	v_fmac_f32_e32 v5, v9, v64
	v_fmac_f32_e32 v2, v9, v65
	v_fmac_f32_e32 v3, v9, v66
	s_waitcnt lgkmcnt(8)
	v_fmac_f32_e32 v0, v32, v68
	v_fmac_f32_e32 v49, v9, v68
	v_add_u32_e32 v80, 0x16800, v62
	v_add_u32_e32 v87, 0x1a000, v62
	v_add_u32_e32 v94, 0x1d800, v62
	v_fmac_f32_e32 v7, v32, v1
	v_fmac_f32_e32 v4, v32, v64
	v_fmac_f32_e32 v5, v32, v65
	v_fmac_f32_e32 v2, v32, v66
	v_fmac_f32_e32 v3, v32, v67
	s_waitcnt lgkmcnt(4)
	v_fmac_f32_e32 v0, v30, v69
	v_fmac_f32_e32 v49, v32, v69
	ds_read_b32 v80, v80
	ds_read_b32 v87, v87
	ds_read_b32 v94, v94
	v_fmac_f32_e32 v6, v30, v1
	v_fmac_f32_e32 v7, v30, v64
	v_fmac_f32_e32 v4, v30, v65
	v_fmac_f32_e32 v5, v30, v66
	v_fmac_f32_e32 v2, v30, v67
	v_fmac_f32_e32 v3, v30, v68
	s_waitcnt lgkmcnt(3)
	v_fmac_f32_e32 v0, v44, v73
	v_fmac_f32_e32 v49, v30, v73
	v_fmac_f32_e32 v11, v44, v1
	v_fmac_f32_e32 v6, v44, v64
	v_fmac_f32_e32 v7, v44, v65
	v_fmac_f32_e32 v4, v44, v66
	v_fmac_f32_e32 v5, v44, v67
	v_fmac_f32_e32 v2, v44, v68
	v_fmac_f32_e32 v3, v44, v69
	v_fmac_f32_e32 v0, v43, v74
	v_fmac_f32_e32 v49, v44, v74
	v_fmac_f32_e32 v10, v43, v1
	v_fmac_f32_e32 v11, v43, v64
	v_fmac_f32_e32 v6, v43, v65
	v_fmac_f32_e32 v7, v43, v66
	v_fmac_f32_e32 v4, v43, v67
	v_fmac_f32_e32 v5, v43, v68
	v_fmac_f32_e32 v2, v43, v69
	v_fmac_f32_e32 v3, v43, v73
	v_fmac_f32_e32 v0, v42, v75
	v_fmac_f32_e32 v49, v43, v75
	v_fmac_f32_e32 v13, v42, v1
	v_fmac_f32_e32 v10, v42, v64
	v_fmac_f32_e32 v11, v42, v65
	v_fmac_f32_e32 v6, v42, v66
	v_fmac_f32_e32 v7, v42, v67
	v_fmac_f32_e32 v4, v42, v68
	v_fmac_f32_e32 v5, v42, v69
	v_fmac_f32_e32 v2, v42, v73
	v_fmac_f32_e32 v3, v42, v74
	v_fmac_f32_e32 v0, v41, v76
	v_fmac_f32_e32 v49, v42, v76
	v_fmac_f32_e32 v12, v41, v1
	v_fmac_f32_e32 v13, v41, v64
	v_fmac_f32_e32 v10, v41, v65
	v_fmac_f32_e32 v11, v41, v66
	v_fmac_f32_e32 v6, v41, v67
	v_fmac_f32_e32 v7, v41, v68
	v_fmac_f32_e32 v4, v41, v69
	v_fmac_f32_e32 v5, v41, v73
	v_fmac_f32_e32 v2, v41, v74
	v_fmac_f32_e32 v3, v41, v75
	v_fmac_f32_e32 v0, v39, v77
	v_fmac_f32_e32 v49, v41, v77
	v_fmac_f32_e32 v15, v39, v1
	v_fmac_f32_e32 v12, v39, v64
	v_fmac_f32_e32 v13, v39, v65
	v_fmac_f32_e32 v10, v39, v66
	v_fmac_f32_e32 v11, v39, v67
	v_fmac_f32_e32 v6, v39, v68
	v_fmac_f32_e32 v7, v39, v69
	v_fmac_f32_e32 v4, v39, v73
	v_fmac_f32_e32 v5, v39, v74
	v_fmac_f32_e32 v2, v39, v75
	v_fmac_f32_e32 v3, v39, v76
	v_fmac_f32_e32 v0, v37, v78
	v_fmac_f32_e32 v49, v39, v78
	v_fmac_f32_e32 v14, v37, v1
	v_fmac_f32_e32 v15, v37, v64
	v_fmac_f32_e32 v12, v37, v65
	v_fmac_f32_e32 v13, v37, v66
	v_fmac_f32_e32 v10, v37, v67
	v_fmac_f32_e32 v11, v37, v68
	v_fmac_f32_e32 v6, v37, v69
	v_fmac_f32_e32 v7, v37, v73
	v_fmac_f32_e32 v4, v37, v74
	v_fmac_f32_e32 v5, v37, v75
	v_fmac_f32_e32 v2, v37, v76
	v_fmac_f32_e32 v3, v37, v77
	v_fmac_f32_e32 v0, v40, v79
	v_fmac_f32_e32 v49, v37, v79
	v_fmac_f32_e32 v17, v40, v1
	v_fmac_f32_e32 v14, v40, v64
	v_fmac_f32_e32 v15, v40, v65
	v_fmac_f32_e32 v12, v40, v66
	v_fmac_f32_e32 v13, v40, v67
	v_fmac_f32_e32 v10, v40, v68
	v_fmac_f32_e32 v11, v40, v69
	v_fmac_f32_e32 v6, v40, v73
	v_fmac_f32_e32 v7, v40, v74
	v_fmac_f32_e32 v4, v40, v75
	v_fmac_f32_e32 v5, v40, v76
	v_fmac_f32_e32 v2, v40, v77
	v_fmac_f32_e32 v3, v40, v78
	s_waitcnt lgkmcnt(2)
	v_fmac_f32_e32 v0, v38, v80
	v_fmac_f32_e32 v49, v40, v80
	v_fmac_f32_e32 v16, v38, v1
	v_fmac_f32_e32 v17, v38, v64
	v_fmac_f32_e32 v14, v38, v65
	v_fmac_f32_e32 v15, v38, v66
	v_fmac_f32_e32 v12, v38, v67
	v_fmac_f32_e32 v13, v38, v68
	v_fmac_f32_e32 v10, v38, v69
	v_fmac_f32_e32 v11, v38, v73
	v_fmac_f32_e32 v6, v38, v74
	v_fmac_f32_e32 v7, v38, v75
	v_fmac_f32_e32 v4, v38, v76
	v_fmac_f32_e32 v5, v38, v77
	v_fmac_f32_e32 v2, v38, v78
	v_fmac_f32_e32 v3, v38, v79
	v_fmac_f32_e32 v0, v53, v81
	v_fmac_f32_e32 v49, v38, v81
	v_fmac_f32_e32 v19, v53, v1
	v_fmac_f32_e32 v16, v53, v64
	v_fmac_f32_e32 v17, v53, v65
	v_fmac_f32_e32 v14, v53, v66
	v_fmac_f32_e32 v15, v53, v67
	v_fmac_f32_e32 v12, v53, v68
	v_fmac_f32_e32 v13, v53, v69
	v_fmac_f32_e32 v10, v53, v73
	v_fmac_f32_e32 v11, v53, v74
	v_fmac_f32_e32 v6, v53, v75
	v_fmac_f32_e32 v7, v53, v76
	v_fmac_f32_e32 v4, v53, v77
	v_fmac_f32_e32 v5, v53, v78
	v_fmac_f32_e32 v2, v53, v79
	v_fmac_f32_e32 v3, v53, v80
	v_fmac_f32_e32 v0, v60, v82
	v_fmac_f32_e32 v49, v53, v82
	v_fmac_f32_e32 v18, v60, v1
	v_fmac_f32_e32 v19, v60, v64
	v_fmac_f32_e32 v16, v60, v65
	v_fmac_f32_e32 v17, v60, v66
	v_fmac_f32_e32 v14, v60, v67
	v_fmac_f32_e32 v15, v60, v68
	v_fmac_f32_e32 v12, v60, v69
	v_fmac_f32_e32 v13, v60, v73
	v_fmac_f32_e32 v10, v60, v74
	v_fmac_f32_e32 v11, v60, v75
	v_fmac_f32_e32 v6, v60, v76
	v_fmac_f32_e32 v7, v60, v77
	v_fmac_f32_e32 v4, v60, v78
	v_fmac_f32_e32 v5, v60, v79
	v_fmac_f32_e32 v2, v60, v80
	v_fmac_f32_e32 v3, v60, v81
	v_fmac_f32_e32 v0, v52, v83
	v_fmac_f32_e32 v49, v60, v83
	v_fmac_f32_e32 v21, v52, v1
	v_fmac_f32_e32 v18, v52, v64
	v_fmac_f32_e32 v19, v52, v65
	v_fmac_f32_e32 v16, v52, v66
	v_fmac_f32_e32 v17, v52, v67
	v_fmac_f32_e32 v14, v52, v68
	v_fmac_f32_e32 v15, v52, v69
	v_fmac_f32_e32 v12, v52, v73
	v_fmac_f32_e32 v13, v52, v74
	v_fmac_f32_e32 v10, v52, v75
	v_fmac_f32_e32 v11, v52, v76
	v_fmac_f32_e32 v6, v52, v77
	v_fmac_f32_e32 v7, v52, v78
	v_fmac_f32_e32 v4, v52, v79
	v_fmac_f32_e32 v5, v52, v80
	v_fmac_f32_e32 v2, v52, v81
	v_fmac_f32_e32 v3, v52, v82
	v_fmac_f32_e32 v0, v51, v84
	v_fmac_f32_e32 v49, v52, v84
	v_fmac_f32_e32 v20, v51, v1
	v_fmac_f32_e32 v21, v51, v64
	v_fmac_f32_e32 v18, v51, v65
	v_fmac_f32_e32 v19, v51, v66
	v_fmac_f32_e32 v16, v51, v67
	v_fmac_f32_e32 v17, v51, v68
; __device__ __forceinline__ void conv_phase(LAS unsigned char* lds, const bf16_t* PROJ, const float* cw, const float* cb, const float* lg, const float* lb, bf16_t* MIXIN, int G, int tid) {
;     ...
;         for (int blk = 0; blk < 4; ++blk) { float win[38];
; #pragma unroll
;             for (int x = 0; x < 38; ++x) win[x] = U[(8 * blk + x) * 512 + c];
; #pragma unroll
;             for (int o = 0; o < 8; ++o) { float acc = bias;
; #pragma unroll
;                 for (int k = 0; k < 31; ++k) acc += w[k] * win[o + k];
;                 y[8 * blk + o] = acc; } }
	v_fmac_f32_e32 v14, v51, v69
	v_fmac_f32_e32 v15, v51, v73
	v_fmac_f32_e32 v12, v51, v74
	v_fmac_f32_e32 v13, v51, v75
	v_fmac_f32_e32 v10, v51, v76
	v_fmac_f32_e32 v11, v51, v77
	v_fmac_f32_e32 v6, v51, v78
	v_fmac_f32_e32 v7, v51, v79
	v_fmac_f32_e32 v4, v51, v80
	v_fmac_f32_e32 v5, v51, v81
	v_fmac_f32_e32 v2, v51, v82
	v_fmac_f32_e32 v3, v51, v83
	v_fmac_f32_e32 v0, v50, v85
	v_fmac_f32_e32 v49, v51, v85
	v_fmac_f32_e32 v23, v50, v1
	v_fmac_f32_e32 v20, v50, v64
	v_fmac_f32_e32 v21, v50, v65
	v_fmac_f32_e32 v18, v50, v66
	v_fmac_f32_e32 v19, v50, v67
	v_fmac_f32_e32 v16, v50, v68
	v_fmac_f32_e32 v17, v50, v69
	v_fmac_f32_e32 v14, v50, v73
	v_fmac_f32_e32 v15, v50, v74
	v_fmac_f32_e32 v12, v50, v75
	v_fmac_f32_e32 v13, v50, v76
	v_fmac_f32_e32 v10, v50, v77
	v_fmac_f32_e32 v11, v50, v78
	v_fmac_f32_e32 v6, v50, v79
	v_fmac_f32_e32 v7, v50, v80
	v_fmac_f32_e32 v4, v50, v81
	v_fmac_f32_e32 v5, v50, v82
	v_fmac_f32_e32 v2, v50, v83
	v_fmac_f32_e32 v3, v50, v84
	v_fmac_f32_e32 v0, v59, v86
	v_fmac_f32_e32 v49, v50, v86
	v_fmac_f32_e32 v22, v59, v1
	v_fmac_f32_e32 v23, v59, v64
	v_fmac_f32_e32 v20, v59, v65
	v_fmac_f32_e32 v21, v59, v66
	v_fmac_f32_e32 v18, v59, v67
	v_fmac_f32_e32 v19, v59, v68
	v_fmac_f32_e32 v16, v59, v69
	v_fmac_f32_e32 v17, v59, v73
	v_fmac_f32_e32 v14, v59, v74
	v_fmac_f32_e32 v15, v59, v75
	v_fmac_f32_e32 v12, v59, v76
	v_fmac_f32_e32 v13, v59, v77
	v_fmac_f32_e32 v10, v59, v78
	v_fmac_f32_e32 v11, v59, v79
	v_fmac_f32_e32 v6, v59, v80
	v_fmac_f32_e32 v7, v59, v81
	v_fmac_f32_e32 v4, v59, v82
	v_fmac_f32_e32 v5, v59, v83
	v_fmac_f32_e32 v2, v59, v84
	v_fmac_f32_e32 v3, v59, v85
	s_waitcnt lgkmcnt(1)
	v_fmac_f32_e32 v0, v47, v87
	v_fmac_f32_e32 v49, v59, v87
	v_fmac_f32_e32 v25, v47, v1
	v_fmac_f32_e32 v22, v47, v64
	v_fmac_f32_e32 v23, v47, v65
	v_fmac_f32_e32 v20, v47, v66
	v_fmac_f32_e32 v21, v47, v67
	v_fmac_f32_e32 v18, v47, v68
	v_fmac_f32_e32 v19, v47, v69
	v_fmac_f32_e32 v16, v47, v73
	v_fmac_f32_e32 v17, v47, v74
	v_fmac_f32_e32 v14, v47, v75
	v_fmac_f32_e32 v15, v47, v76
	v_fmac_f32_e32 v12, v47, v77
	v_fmac_f32_e32 v13, v47, v78
	v_fmac_f32_e32 v10, v47, v79
	v_fmac_f32_e32 v11, v47, v80
	v_fmac_f32_e32 v6, v47, v81
	v_fmac_f32_e32 v7, v47, v82
	v_fmac_f32_e32 v4, v47, v83
	v_fmac_f32_e32 v5, v47, v84
	v_fmac_f32_e32 v2, v47, v85
	v_fmac_f32_e32 v3, v47, v86
	v_fmac_f32_e32 v0, v46, v88
	v_fmac_f32_e32 v49, v47, v88
	v_fmac_f32_e32 v24, v46, v1
	v_fmac_f32_e32 v25, v46, v64
	v_fmac_f32_e32 v22, v46, v65
	v_fmac_f32_e32 v23, v46, v66
	v_fmac_f32_e32 v20, v46, v67
	v_fmac_f32_e32 v21, v46, v68
	v_fmac_f32_e32 v18, v46, v69
	v_fmac_f32_e32 v19, v46, v73
	v_fmac_f32_e32 v16, v46, v74
	v_fmac_f32_e32 v17, v46, v75
	v_fmac_f32_e32 v14, v46, v76
	v_fmac_f32_e32 v15, v46, v77
	v_fmac_f32_e32 v12, v46, v78
	v_fmac_f32_e32 v13, v46, v79
	v_fmac_f32_e32 v10, v46, v80
	v_fmac_f32_e32 v11, v46, v81
	v_fmac_f32_e32 v6, v46, v82
	v_fmac_f32_e32 v7, v46, v83
	v_fmac_f32_e32 v4, v46, v84
	v_fmac_f32_e32 v5, v46, v85
	v_fmac_f32_e32 v2, v46, v86
	v_fmac_f32_e32 v3, v46, v87
	v_fmac_f32_e32 v0, v48, v89
	v_fmac_f32_e32 v49, v46, v89
	v_fmac_f32_e32 v27, v48, v1
	v_fmac_f32_e32 v24, v48, v64
	v_fmac_f32_e32 v25, v48, v65
	v_fmac_f32_e32 v22, v48, v66
	v_fmac_f32_e32 v23, v48, v67
	v_fmac_f32_e32 v20, v48, v68
	v_fmac_f32_e32 v21, v48, v69
	v_fmac_f32_e32 v18, v48, v73
	v_fmac_f32_e32 v19, v48, v74
	v_fmac_f32_e32 v16, v48, v75
	v_fmac_f32_e32 v17, v48, v76
	v_fmac_f32_e32 v14, v48, v77
	v_fmac_f32_e32 v15, v48, v78
	v_fmac_f32_e32 v12, v48, v79
	v_fmac_f32_e32 v13, v48, v80
	v_fmac_f32_e32 v10, v48, v81
	v_fmac_f32_e32 v11, v48, v82
	v_fmac_f32_e32 v6, v48, v83
	v_fmac_f32_e32 v7, v48, v84
	v_fmac_f32_e32 v4, v48, v85
	v_fmac_f32_e32 v5, v48, v86
	v_fmac_f32_e32 v2, v48, v87
	v_fmac_f32_e32 v3, v48, v88
	v_fmac_f32_e32 v0, v56, v90
	v_fmac_f32_e32 v49, v48, v90
	v_fmac_f32_e32 v26, v56, v1
	v_fmac_f32_e32 v27, v56, v64
	v_fmac_f32_e32 v24, v56, v65
	v_fmac_f32_e32 v25, v56, v66
	v_fmac_f32_e32 v22, v56, v67
	v_fmac_f32_e32 v23, v56, v68
	v_fmac_f32_e32 v20, v56, v69
	v_fmac_f32_e32 v21, v56, v73
	v_fmac_f32_e32 v18, v56, v74
	v_fmac_f32_e32 v19, v56, v75
	v_fmac_f32_e32 v16, v56, v76
	v_fmac_f32_e32 v17, v56, v77
	v_fmac_f32_e32 v14, v56, v78
	v_fmac_f32_e32 v15, v56, v79
	v_fmac_f32_e32 v12, v56, v80
	v_fmac_f32_e32 v13, v56, v81
	v_fmac_f32_e32 v10, v56, v82
	v_fmac_f32_e32 v11, v56, v83
	v_fmac_f32_e32 v6, v56, v84
	v_fmac_f32_e32 v7, v56, v85
	v_fmac_f32_e32 v4, v56, v86
	v_fmac_f32_e32 v5, v56, v87
	v_fmac_f32_e32 v2, v56, v88
	v_fmac_f32_e32 v3, v56, v89
	v_fmac_f32_e32 v0, v45, v91
	v_fmac_f32_e32 v49, v56, v91
	v_fmac_f32_e32 v29, v45, v1
	v_fmac_f32_e32 v26, v45, v64
	v_fmac_f32_e32 v27, v45, v65
	v_fmac_f32_e32 v24, v45, v66
	v_fmac_f32_e32 v25, v45, v67
	v_fmac_f32_e32 v22, v45, v68
	v_fmac_f32_e32 v23, v45, v69
	v_fmac_f32_e32 v20, v45, v73
	v_fmac_f32_e32 v21, v45, v74
	v_fmac_f32_e32 v18, v45, v75
	v_fmac_f32_e32 v19, v45, v76
	v_fmac_f32_e32 v16, v45, v77
	v_fmac_f32_e32 v17, v45, v78
	v_fmac_f32_e32 v14, v45, v79
	v_fmac_f32_e32 v15, v45, v80
	v_fmac_f32_e32 v12, v45, v81
	v_fmac_f32_e32 v13, v45, v82
	v_fmac_f32_e32 v10, v45, v83
	v_fmac_f32_e32 v11, v45, v84
	v_fmac_f32_e32 v6, v45, v85
	v_fmac_f32_e32 v7, v45, v86
	v_fmac_f32_e32 v4, v45, v87
	v_fmac_f32_e32 v5, v45, v88
	v_fmac_f32_e32 v2, v45, v89
	v_fmac_f32_e32 v3, v45, v90
	v_fmac_f32_e32 v0, v58, v92
	v_fmac_f32_e32 v49, v45, v92
	v_fmac_f32_e32 v28, v58, v1
	v_fmac_f32_e32 v29, v58, v64
	v_fmac_f32_e32 v26, v58, v65
	v_fmac_f32_e32 v27, v58, v66
	v_fmac_f32_e32 v24, v58, v67
	v_fmac_f32_e32 v25, v58, v68
	v_fmac_f32_e32 v22, v58, v69
; __device__ __forceinline__ void conv_phase(LAS unsigned char* lds, const bf16_t* PROJ, const float* cw, const float* cb, const float* lg, const float* lb, bf16_t* MIXIN, int G, int tid) {
;     ...
;         for (int blk = 0; blk < 4; ++blk) { float win[38];
; #pragma unroll
;             for (int x = 0; x < 38; ++x) win[x] = U[(8 * blk + x) * 512 + c];
; #pragma unroll
;             for (int o = 0; o < 8; ++o) { float acc = bias;
; #pragma unroll
;                 for (int k = 0; k < 31; ++k) acc += w[k] * win[o + k];
;                 y[8 * blk + o] = acc; } }
;         __syncthreads();
; #pragma unroll
;         for (int tt = 0; tt < 32; ++tt) U[tt * 512 + c] = y[tt];
;         __syncthreads();
	v_fmac_f32_e32 v23, v58, v73
	v_fmac_f32_e32 v20, v58, v74
	v_fmac_f32_e32 v21, v58, v75
	v_fmac_f32_e32 v18, v58, v76
	v_fmac_f32_e32 v19, v58, v77
	v_fmac_f32_e32 v16, v58, v78
	v_fmac_f32_e32 v17, v58, v79
	v_fmac_f32_e32 v14, v58, v80
	v_fmac_f32_e32 v15, v58, v81
	v_fmac_f32_e32 v12, v58, v82
	v_fmac_f32_e32 v13, v58, v83
	v_fmac_f32_e32 v10, v58, v84
	v_fmac_f32_e32 v11, v58, v85
	v_fmac_f32_e32 v6, v58, v86
	v_fmac_f32_e32 v7, v58, v87
	v_fmac_f32_e32 v4, v58, v88
	v_fmac_f32_e32 v5, v58, v89
	v_fmac_f32_e32 v2, v58, v90
	v_fmac_f32_e32 v3, v58, v91
	v_fmac_f32_e32 v0, v57, v93
	v_fmac_f32_e32 v49, v58, v93
	v_fmac_f32_e32 v72, v57, v1
	v_fmac_f32_e32 v28, v57, v64
	v_fmac_f32_e32 v29, v57, v65
	v_fmac_f32_e32 v26, v57, v66
	v_fmac_f32_e32 v27, v57, v67
	v_fmac_f32_e32 v24, v57, v68
	v_fmac_f32_e32 v25, v57, v69
	v_fmac_f32_e32 v22, v57, v73
	v_fmac_f32_e32 v23, v57, v74
	v_fmac_f32_e32 v20, v57, v75
	v_fmac_f32_e32 v21, v57, v76
	v_fmac_f32_e32 v18, v57, v77
	v_fmac_f32_e32 v19, v57, v78
	v_fmac_f32_e32 v16, v57, v79
	v_fmac_f32_e32 v17, v57, v80
	v_fmac_f32_e32 v14, v57, v81
	v_fmac_f32_e32 v15, v57, v82
	v_fmac_f32_e32 v12, v57, v83
	v_fmac_f32_e32 v13, v57, v84
	v_fmac_f32_e32 v10, v57, v85
	v_fmac_f32_e32 v11, v57, v86
	v_fmac_f32_e32 v6, v57, v87
	v_fmac_f32_e32 v7, v57, v88
	v_fmac_f32_e32 v4, v57, v89
	v_fmac_f32_e32 v5, v57, v90
	v_fmac_f32_e32 v2, v57, v91
	v_fmac_f32_e32 v3, v57, v92
	s_waitcnt lgkmcnt(0)
	v_fmac_f32_e32 v0, v54, v94
	v_fmac_f32_e32 v49, v57, v94
	v_fmac_f32_e32 v70, v55, v1
	v_fmac_f32_e32 v71, v54, v1
	v_fmac_f32_e32 v72, v54, v64
	v_fmac_f32_e32 v28, v54, v65
	v_fmac_f32_e32 v29, v54, v66
	v_fmac_f32_e32 v26, v54, v67
	v_fmac_f32_e32 v27, v54, v68
	v_fmac_f32_e32 v24, v54, v69
	v_fmac_f32_e32 v25, v54, v73
	v_fmac_f32_e32 v22, v54, v74
	v_fmac_f32_e32 v23, v54, v75
	v_fmac_f32_e32 v20, v54, v76
	v_fmac_f32_e32 v21, v54, v77
	v_fmac_f32_e32 v18, v54, v78
	v_fmac_f32_e32 v19, v54, v79
	v_fmac_f32_e32 v16, v54, v80
	v_fmac_f32_e32 v17, v54, v81
	v_fmac_f32_e32 v14, v54, v82
	v_fmac_f32_e32 v15, v54, v83
	v_fmac_f32_e32 v12, v54, v84
	v_fmac_f32_e32 v13, v54, v85
	v_fmac_f32_e32 v10, v54, v86
	v_fmac_f32_e32 v11, v54, v87
	v_fmac_f32_e32 v6, v54, v88
	v_fmac_f32_e32 v7, v54, v89
	v_fmac_f32_e32 v4, v54, v90
	v_fmac_f32_e32 v5, v54, v91
	v_fmac_f32_e32 v2, v54, v92
	v_fmac_f32_e32 v3, v54, v93
	v_fmac_f32_e32 v0, v55, v95
	v_fmac_f32_e32 v49, v54, v95
	v_fmac_f32_e32 v71, v55, v64
	v_fmac_f32_e32 v72, v55, v65
	v_fmac_f32_e32 v28, v55, v66
	v_fmac_f32_e32 v29, v55, v67
	v_fmac_f32_e32 v26, v55, v68
	v_fmac_f32_e32 v27, v55, v69
	v_fmac_f32_e32 v24, v55, v73
	v_fmac_f32_e32 v25, v55, v74
	v_fmac_f32_e32 v22, v55, v75
	v_fmac_f32_e32 v23, v55, v76
	v_fmac_f32_e32 v20, v55, v77
	v_fmac_f32_e32 v21, v55, v78
	v_fmac_f32_e32 v18, v55, v79
	v_fmac_f32_e32 v19, v55, v80
	v_fmac_f32_e32 v16, v55, v81
	v_fmac_f32_e32 v17, v55, v82
	v_fmac_f32_e32 v14, v55, v83
	v_fmac_f32_e32 v15, v55, v84
	v_fmac_f32_e32 v12, v55, v85
	v_fmac_f32_e32 v13, v55, v86
	v_fmac_f32_e32 v10, v55, v87
	v_fmac_f32_e32 v11, v55, v88
	v_fmac_f32_e32 v6, v55, v89
	v_fmac_f32_e32 v7, v55, v90
	v_fmac_f32_e32 v4, v55, v91
	v_fmac_f32_e32 v5, v55, v92
	v_fmac_f32_e32 v2, v55, v93
	v_fmac_f32_e32 v3, v55, v94
	v_fmac_f32_e32 v49, v55, v96
	s_barrier
	ds_write2st64_b32 v62, v63, v70 offset1:8
	ds_write2st64_b32 v62, v71, v72 offset0:16 offset1:24
	ds_write2st64_b32 v62, v28, v29 offset0:32 offset1:40
	ds_write2st64_b32 v62, v26, v27 offset0:48 offset1:56
	ds_write2st64_b32 v62, v24, v25 offset0:64 offset1:72
	ds_write2st64_b32 v62, v22, v23 offset0:80 offset1:88
	ds_write2st64_b32 v62, v20, v21 offset0:96 offset1:104
	ds_write2st64_b32 v62, v18, v19 offset0:112 offset1:120
	ds_write2st64_b32 v62, v16, v17 offset0:128 offset1:136
	ds_write2st64_b32 v62, v14, v15 offset0:144 offset1:152
	ds_write2st64_b32 v62, v12, v13 offset0:160 offset1:168
	ds_write2st64_b32 v62, v10, v11 offset0:176 offset1:184
	ds_write2st64_b32 v62, v6, v7 offset0:192 offset1:200
	ds_write2st64_b32 v62, v4, v5 offset0:208 offset1:216
	ds_write2st64_b32 v62, v2, v3 offset0:224 offset1:232
	ds_write2st64_b32 v62, v0, v49 offset0:240 offset1:248
	v_and_b32_e32 v0, 64, v230
	v_add_u32_e32 v0, 64, v0
	v_xor_b32_e32 v1, 1, v230
	v_cmp_lt_i32_e32 vcc, v1, v0
	s_lshl_b32 s5, s4, 2
	s_lshl_b32 s4, s4, 13
	v_cndmask_b32_e32 v1, v230, v1, vcc
	v_lshlrev_b32_e32 v13, 2, v1
	v_xor_b32_e32 v1, 2, v230
	v_cmp_lt_i32_e32 vcc, v1, v0
	v_lshlrev_b32_e32 v9, 2, v61
	s_add_i32 s4, s4, 0
	v_cndmask_b32_e32 v1, v230, v1, vcc
	v_lshlrev_b32_e32 v18, 2, v1
	v_xor_b32_e32 v1, 4, v230
	v_cmp_lt_i32_e32 vcc, v1, v0
	v_add_u32_e32 v23, s4, v9
	s_waitcnt lgkmcnt(0)
	v_cndmask_b32_e32 v1, v230, v1, vcc
	v_lshlrev_b32_e32 v19, 2, v1
	v_xor_b32_e32 v1, 8, v230
	v_cmp_lt_i32_e32 vcc, v1, v0
	s_barrier
; __device__ __forceinline__ u32x4 pack8(const f32x4 v0, const f32x4 v1) { u32x4 w; w.x = cvt_pk_bf16(v0[0], v0[1]); w.y = cvt_pk_bf16(v0[2], v0[3]); w.z = cvt_pk_bf16(v1[0], v1[1]); w.w = cvt_pk_bf16(v1[2], v1[3]); return w; }
; __device__ __forceinline__ float silu_fast(float x) { return x * __builtin_amdgcn_rcpf(1.f + __expf(-x)); }
; #define LAS __attribute__((address_space(3)))
; __device__ __forceinline__ void conv_phase(LAS unsigned char* lds, const bf16_t* PROJ, const float* cw, const float* cb, const float* lg, const float* lb, bf16_t* MIXIN, int G, int tid) {
;     ...
;         for (int q = 0; q < 4; ++q) { const int tt = 4 * wave + q;
;             f32x4 a = *(const LAS f32x4*)(U + tt * 512 + 8 * lane), b = *(const LAS f32x4*)(U + tt * 512 + 8 * lane + 4);
;             const float mean = wave_sum((a[0] + a[1]) + (a[2] + a[3]) + (b[0] + b[1]) + (b[2] + b[3])) * (1.f / 512.f);
;             a = a - mean; b = b - mean;
;             const float var = wave_sum((a[0] * a[0] + a[1] * a[1]) + (a[2] * a[2] + a[3] * a[3]) + (b[0] * b[0] + b[1] * b[1]) + (b[2] * b[2] + b[3] * b[3])) * (1.f / 512.f);
;             const float rstd = rsqrtf(var + LN_EPS);
;             a = a * rstd * *(const f32x4*)(lg + 8 * lane) + *(const f32x4*)(lb + 8 * lane); b = b * rstd * *(const f32x4*)(lg + 8 * lane + 4) + *(const f32x4*)(lb + 8 * lane + 4);
; #pragma unroll
;             for (int x = 0; x < 4; ++x) { a[x] = pg8::silu_fast(a[x]); b[x] = pg8::silu_fast(b[x]); }
;             *(u32x4*)(MIXIN + (size_t)(row0 + tt) * D + 8 * lane) = pg8::pack8(a, b); }
	s_nop 0
	v_cndmask_b32_e32 v1, v230, v1, vcc
	v_lshlrev_b32_e32 v20, 2, v1
	v_xor_b32_e32 v1, 16, v230
	v_cmp_lt_i32_e32 vcc, v1, v0
	v_readlane_b32 s18, v250, 10
	s_add_i32 s4, s6, s5
	v_cndmask_b32_e32 v1, v230, v1, vcc
	v_lshlrev_b32_e32 v21, 2, v1
	v_xor_b32_e32 v1, 32, v230
	v_cmp_lt_i32_e32 vcc, v1, v0
	v_lshlrev_b32_e32 v164, 1, v61
	v_readlane_b32 s19, v250, 11
	v_cndmask_b32_e32 v0, v230, v1, vcc
	v_lshlrev_b32_e32 v22, 2, v0
	ds_read_b128 v[4:7], v23
	ds_read_b128 v[0:3], v23 offset:16
	s_ashr_i32 s5, s4, 31
	v_lshl_add_u64 v[10:11], s[18:19], 0, v[164:165]
	s_lshl_b64 s[18:19], s[4:5], 11
	s_waitcnt lgkmcnt(1)
	v_mov_b32_e32 v14, v5
	v_mov_b32_e32 v15, v6
	v_mov_b32_e32 v16, v4
	v_mov_b32_e32 v17, v7
	v_pk_add_f32 v[14:15], v[14:15], v[16:17]
	s_waitcnt lgkmcnt(0)
	v_mov_b32_e32 v16, v2
	v_mov_b32_e32 v17, v0
	v_mov_b32_e32 v24, v3
	v_mov_b32_e32 v25, v1
	v_pk_add_f32 v[16:17], v[16:17], v[24:25]
	v_add_f32_e32 v12, v14, v15
	v_add_f32_e32 v12, v12, v17
	v_add_f32_e32 v12, v16, v12
	s_add_i32 s7, s7, s50
	s_nop 1
	v_add_f32_dpp v14, v12, v12 quad_perm:[1,0,3,2] row_mask:0xf bank_mask:0xf
	s_nop 1
	v_add_f32_dpp v12, v14, v14 quad_perm:[2,3,0,1] row_mask:0xf bank_mask:0xf
	s_nop 1
	v_add_f32_dpp v14, v12, v12 row_half_mirror row_mask:0xf bank_mask:0xf
	s_nop 1
	v_add_f32_dpp v12, v14, v14 row_mirror row_mask:0xf bank_mask:0xf
	s_nop 0
	v_readlane_b32 s14, v12, 0
	v_readlane_b32 s15, v12, 16
	v_readlane_b32 s16, v12, 32
	v_readlane_b32 s17, v12, 48
	s_nop 1
	v_mov_b32_e32 v14, s15
	v_add_f32_e32 v14, s14, v14
	v_mov_b32_e32 v12, s17
	v_add_f32_e32 v12, s16, v12
	v_add_f32_e32 v12, v14, v12
	v_fmamk_f32 v5, v12, 0xbb000000, v5
	v_fmamk_f32 v4, v12, 0xbb000000, v4
	v_fmamk_f32 v7, v12, 0xbb000000, v7
	v_fmac_f32_e32 v6, 0xbb000000, v12
	v_pk_mul_f32 v[14:15], v[6:7], v[6:7]
	v_pk_mul_f32 v[16:17], v[4:5], v[4:5]
	v_fmamk_f32 v1, v12, 0xbb000000, v1
	v_fmamk_f32 v0, v12, 0xbb000000, v0
	v_fmamk_f32 v3, v12, 0xbb000000, v3
	v_fmac_f32_e32 v2, 0xbb000000, v12
	v_pk_mov_b32 v[24:25], v[16:17], v[14:15] op_sel:[1,0]
	v_mov_b32_e32 v17, v15
	v_pk_add_f32 v[14:15], v[24:25], v[16:17]
	v_pk_mul_f32 v[16:17], v[2:3], v[2:3]
	v_pk_mul_f32 v[24:25], v[0:1], v[0:1]
	v_mov_b32_e32 v26, v16
	v_mov_b32_e32 v27, v24
	v_mov_b32_e32 v24, v17
	v_pk_add_f32 v[16:17], v[26:27], v[24:25]
	v_add_f32_e32 v12, v14, v15
	v_add_f32_e32 v12, v17, v12
	v_add_f32_e32 v12, v16, v12
	s_nop 1
	v_add_f32_dpp v14, v12, v12 quad_perm:[1,0,3,2] row_mask:0xf bank_mask:0xf
	s_nop 1
	v_add_f32_dpp v12, v14, v14 quad_perm:[2,3,0,1] row_mask:0xf bank_mask:0xf
	s_nop 1
	v_add_f32_dpp v14, v12, v12 row_half_mirror row_mask:0xf bank_mask:0xf
	s_nop 1
	v_add_f32_dpp v12, v14, v14 row_mirror row_mask:0xf bank_mask:0xf
	s_nop 0
	v_readlane_b32 s14, v12, 0
	v_readlane_b32 s15, v12, 16
	v_readlane_b32 s16, v12, 32
	v_readlane_b32 s17, v12, 48
	s_nop 1
	v_mov_b32_e32 v14, s15
	v_add_f32_e32 v14, s14, v14
	v_mov_b32_e32 v12, s17
	v_add_f32_e32 v12, s16, v12
	v_add_f32_e32 v12, v14, v12
	v_fmamk_f32 v12, v12, 0x3b000000, v173
	v_cmp_gt_f32_e32 vcc, s81, v12
	v_mul_f32_e32 v14, 0x4b800000, v12
	s_nop 0
	v_cndmask_b32_e32 v12, v12, v14, vcc
	v_rsq_f32_e32 v12, v12
	s_nop 0
	v_mul_f32_e32 v14, 0x45800000, v12
	v_cndmask_b32_e32 v12, v12, v14, vcc
	v_pk_mul_f32 v[14:15], v[4:5], v[12:13] op_sel_hi:[1,0]
	v_pk_mul_f32 v[16:17], v[6:7], v[12:13] op_sel_hi:[1,0]
	v_pk_mul_f32 v[0:1], v[0:1], v[12:13] op_sel_hi:[1,0]
	v_pk_mul_f32 v[2:3], v[2:3], v[12:13] op_sel_hi:[1,0]
	v_pk_fma_f32 v[0:1], v[100:101], v[0:1], v[108:109]
	v_pk_fma_f32 v[2:3], v[102:103], v[2:3], v[110:111]
	v_mul_f32_e32 v5, 0xbfb8aa3b, v0
	v_mul_f32_e32 v6, 0xbfb8aa3b, v1
	v_mul_f32_e32 v7, 0xbfb8aa3b, v2
	v_exp_f32_e32 v5, v5
	v_exp_f32_e32 v6, v6
	v_exp_f32_e32 v7, v7
	v_pk_fma_f32 v[16:17], v[106:107], v[16:17], v[114:115]
	v_add_f32_e32 v5, 1.0, v5
	v_add_f32_e32 v6, 1.0, v6
	v_add_f32_e32 v7, 1.0, v7
	v_rcp_f32_e32 v5, v5
	v_rcp_f32_e32 v6, v6
	v_rcp_f32_e32 v7, v7
	v_pk_fma_f32 v[14:15], v[104:105], v[14:15], v[112:113]
	v_mul_f32_e32 v5, v0, v5
	v_mul_f32_e32 v4, 0xbfb8aa3b, v14
	v_mul_f32_e32 v0, 0xbfb8aa3b, v15
	v_mul_f32_e32 v6, v1, v6
	v_mul_f32_e32 v1, 0xbfb8aa3b, v16
	v_mul_f32_e32 v7, v2, v7
	v_mul_f32_e32 v2, 0xbfb8aa3b, v17
	v_exp_f32_e32 v4, v4
	v_exp_f32_e32 v0, v0
	v_exp_f32_e32 v1, v1
	v_exp_f32_e32 v2, v2
	v_mul_f32_e32 v12, 0xbfb8aa3b, v3
	v_exp_f32_e32 v12, v12
	v_add_f32_e32 v4, 1.0, v4
	v_add_f32_e32 v0, 1.0, v0
	v_add_f32_e32 v1, 1.0, v1
	v_add_f32_e32 v2, 1.0, v2
	v_rcp_f32_e32 v4, v4
	v_rcp_f32_e32 v0, v0
	v_rcp_f32_e32 v1, v1
	v_rcp_f32_e32 v2, v2
	v_add_f32_e32 v12, 1.0, v12
	v_rcp_f32_e32 v12, v12
	v_mul_f32_e32 v4, v14, v4
	v_mul_f32_e32 v0, v15, v0
	v_mul_f32_e32 v1, v16, v1
	v_mul_f32_e32 v2, v17, v2
	v_mul_f32_e32 v3, v3, v12
	v_cvt_pk_bf16_f32 v0, v4, v0
	v_cvt_pk_bf16_f32 v1, v1, v2
	v_cvt_pk_bf16_f32 v2, v5, v6
	v_lshl_add_u64 v[4:5], v[10:11], 0, s[18:19]
	v_cvt_pk_bf16_f32 v3, v7, v3
	global_store_dwordx4 v[4:5], v[0:3], off
	ds_read_b128 v[4:7], v23 offset:2048
	ds_read_b128 v[0:3], v23 offset:2064
	s_add_i32 s18, s4, 1
	s_ashr_i32 s19, s18, 31
	s_lshl_b64 s[18:19], s[18:19], 11
	s_waitcnt lgkmcnt(1)
	v_mov_b32_e32 v14, v5
	v_mov_b32_e32 v15, v6
	v_mov_b32_e32 v16, v4
	v_mov_b32_e32 v17, v7
	v_pk_add_f32 v[14:15], v[14:15], v[16:17]
	s_waitcnt lgkmcnt(0)
; __device__ __forceinline__ u32x4 pack8(const f32x4 v0, const f32x4 v1) { u32x4 w; w.x = cvt_pk_bf16(v0[0], v0[1]); w.y = cvt_pk_bf16(v0[2], v0[3]); w.z = cvt_pk_bf16(v1[0], v1[1]); w.w = cvt_pk_bf16(v1[2], v1[3]); return w; }
; __device__ __forceinline__ float silu_fast(float x) { return x * __builtin_amdgcn_rcpf(1.f + __expf(-x)); }
; #define LAS __attribute__((address_space(3)))
; __device__ __forceinline__ void conv_phase(LAS unsigned char* lds, const bf16_t* PROJ, const float* cw, const float* cb, const float* lg, const float* lb, bf16_t* MIXIN, int G, int tid) {
;     ...
;         for (int q = 0; q < 4; ++q) { const int tt = 4 * wave + q;
;             f32x4 a = *(const LAS f32x4*)(U + tt * 512 + 8 * lane), b = *(const LAS f32x4*)(U + tt * 512 + 8 * lane + 4);
;             const float mean = wave_sum((a[0] + a[1]) + (a[2] + a[3]) + (b[0] + b[1]) + (b[2] + b[3])) * (1.f / 512.f);
;             a = a - mean; b = b - mean;
;             const float var = wave_sum((a[0] * a[0] + a[1] * a[1]) + (a[2] * a[2] + a[3] * a[3]) + (b[0] * b[0] + b[1] * b[1]) + (b[2] * b[2] + b[3] * b[3])) * (1.f / 512.f);
;             const float rstd = rsqrtf(var + LN_EPS);
;             a = a * rstd * *(const f32x4*)(lg + 8 * lane) + *(const f32x4*)(lb + 8 * lane); b = b * rstd * *(const f32x4*)(lg + 8 * lane + 4) + *(const f32x4*)(lb + 8 * lane + 4);
; #pragma unroll
;             for (int x = 0; x < 4; ++x) { a[x] = pg8::silu_fast(a[x]); b[x] = pg8::silu_fast(b[x]); }
;             *(u32x4*)(MIXIN + (size_t)(row0 + tt) * D + 8 * lane) = pg8::pack8(a, b); }
	v_mov_b32_e32 v16, v2
	v_mov_b32_e32 v17, v0
	v_mov_b32_e32 v24, v3
	v_mov_b32_e32 v25, v1
	v_pk_add_f32 v[16:17], v[16:17], v[24:25]
	v_add_f32_e32 v12, v14, v15
	v_add_f32_e32 v12, v12, v17
	v_add_f32_e32 v12, v16, v12
	s_nop 1
	v_add_f32_dpp v14, v12, v12 quad_perm:[1,0,3,2] row_mask:0xf bank_mask:0xf
	s_nop 1
	v_add_f32_dpp v12, v14, v14 quad_perm:[2,3,0,1] row_mask:0xf bank_mask:0xf
	s_nop 1
	v_add_f32_dpp v14, v12, v12 row_half_mirror row_mask:0xf bank_mask:0xf
	s_nop 1
	v_add_f32_dpp v12, v14, v14 row_mirror row_mask:0xf bank_mask:0xf
	s_nop 0
	v_readlane_b32 s14, v12, 0
	v_readlane_b32 s15, v12, 16
	v_readlane_b32 s16, v12, 32
	v_readlane_b32 s17, v12, 48
	s_nop 1
	v_mov_b32_e32 v14, s15
	v_add_f32_e32 v14, s14, v14
	v_mov_b32_e32 v12, s17
	v_add_f32_e32 v12, s16, v12
	v_add_f32_e32 v12, v14, v12
	v_fmamk_f32 v5, v12, 0xbb000000, v5
	v_fmamk_f32 v4, v12, 0xbb000000, v4
	v_fmamk_f32 v7, v12, 0xbb000000, v7
	v_fmac_f32_e32 v6, 0xbb000000, v12
	v_pk_mul_f32 v[14:15], v[6:7], v[6:7]
	v_pk_mul_f32 v[16:17], v[4:5], v[4:5]
	v_fmamk_f32 v1, v12, 0xbb000000, v1
	v_fmamk_f32 v0, v12, 0xbb000000, v0
	v_fmamk_f32 v3, v12, 0xbb000000, v3
	v_fmac_f32_e32 v2, 0xbb000000, v12
	v_pk_mov_b32 v[24:25], v[16:17], v[14:15] op_sel:[1,0]
	v_mov_b32_e32 v17, v15
	v_pk_add_f32 v[14:15], v[24:25], v[16:17]
	v_pk_mul_f32 v[16:17], v[2:3], v[2:3]
	v_pk_mul_f32 v[24:25], v[0:1], v[0:1]
	v_mov_b32_e32 v26, v16
	v_mov_b32_e32 v27, v24
	v_mov_b32_e32 v24, v17
	v_pk_add_f32 v[16:17], v[26:27], v[24:25]
	v_add_f32_e32 v12, v14, v15
	v_add_f32_e32 v12, v17, v12
	v_add_f32_e32 v12, v16, v12
	s_nop 1
	v_add_f32_dpp v14, v12, v12 quad_perm:[1,0,3,2] row_mask:0xf bank_mask:0xf
	s_nop 1
	v_add_f32_dpp v12, v14, v14 quad_perm:[2,3,0,1] row_mask:0xf bank_mask:0xf
	s_nop 1
	v_add_f32_dpp v14, v12, v12 row_half_mirror row_mask:0xf bank_mask:0xf
	s_nop 1
	v_add_f32_dpp v12, v14, v14 row_mirror row_mask:0xf bank_mask:0xf
	s_nop 0
	v_readlane_b32 s14, v12, 0
	v_readlane_b32 s15, v12, 16
	v_readlane_b32 s16, v12, 32
	v_readlane_b32 s17, v12, 48
	s_nop 1
	v_mov_b32_e32 v14, s15
	v_add_f32_e32 v14, s14, v14
	v_mov_b32_e32 v12, s17
	v_add_f32_e32 v12, s16, v12
	v_add_f32_e32 v12, v14, v12
	v_fmamk_f32 v12, v12, 0x3b000000, v173
	v_cmp_gt_f32_e32 vcc, s81, v12
	v_mul_f32_e32 v14, 0x4b800000, v12
	s_nop 0
	v_cndmask_b32_e32 v12, v12, v14, vcc
	v_rsq_f32_e32 v12, v12
	s_nop 0
	v_mul_f32_e32 v14, 0x45800000, v12
	v_cndmask_b32_e32 v12, v12, v14, vcc
	v_pk_mul_f32 v[14:15], v[4:5], v[12:13] op_sel_hi:[1,0]
	v_pk_mul_f32 v[16:17], v[6:7], v[12:13] op_sel_hi:[1,0]
	v_pk_mul_f32 v[0:1], v[0:1], v[12:13] op_sel_hi:[1,0]
	v_pk_mul_f32 v[2:3], v[2:3], v[12:13] op_sel_hi:[1,0]
	v_pk_fma_f32 v[0:1], v[100:101], v[0:1], v[108:109]
	v_pk_fma_f32 v[2:3], v[102:103], v[2:3], v[110:111]
	v_mul_f32_e32 v5, 0xbfb8aa3b, v0
	v_mul_f32_e32 v6, 0xbfb8aa3b, v1
	v_mul_f32_e32 v7, 0xbfb8aa3b, v2
	v_exp_f32_e32 v5, v5
	v_exp_f32_e32 v6, v6
	v_exp_f32_e32 v7, v7
	v_pk_fma_f32 v[16:17], v[106:107], v[16:17], v[114:115]
	v_add_f32_e32 v5, 1.0, v5
	v_add_f32_e32 v6, 1.0, v6
	v_add_f32_e32 v7, 1.0, v7
	v_rcp_f32_e32 v5, v5
	v_rcp_f32_e32 v6, v6
	v_rcp_f32_e32 v7, v7
	v_pk_fma_f32 v[14:15], v[104:105], v[14:15], v[112:113]
	v_mul_f32_e32 v5, v0, v5
	v_mul_f32_e32 v4, 0xbfb8aa3b, v14
	v_mul_f32_e32 v0, 0xbfb8aa3b, v15
	v_mul_f32_e32 v6, v1, v6
	v_mul_f32_e32 v1, 0xbfb8aa3b, v16
	v_mul_f32_e32 v7, v2, v7
	v_mul_f32_e32 v2, 0xbfb8aa3b, v17
	v_exp_f32_e32 v4, v4
	v_exp_f32_e32 v0, v0
	v_exp_f32_e32 v1, v1
	v_exp_f32_e32 v2, v2
	v_mul_f32_e32 v12, 0xbfb8aa3b, v3
	v_exp_f32_e32 v12, v12
	v_add_f32_e32 v4, 1.0, v4
	v_add_f32_e32 v0, 1.0, v0
	v_add_f32_e32 v1, 1.0, v1
	v_add_f32_e32 v2, 1.0, v2
	v_rcp_f32_e32 v4, v4
	v_rcp_f32_e32 v0, v0
	v_rcp_f32_e32 v1, v1
	v_rcp_f32_e32 v2, v2
	v_add_f32_e32 v12, 1.0, v12
	v_rcp_f32_e32 v12, v12
	v_mul_f32_e32 v4, v14, v4
	v_mul_f32_e32 v0, v15, v0
	v_mul_f32_e32 v1, v16, v1
	v_mul_f32_e32 v2, v17, v2
	v_mul_f32_e32 v3, v3, v12
	v_cvt_pk_bf16_f32 v0, v4, v0
	v_cvt_pk_bf16_f32 v1, v1, v2
	v_cvt_pk_bf16_f32 v2, v5, v6
	v_lshl_add_u64 v[4:5], v[10:11], 0, s[18:19]
	v_cvt_pk_bf16_f32 v3, v7, v3
	global_store_dwordx4 v[4:5], v[0:3], off
	ds_read_b128 v[4:7], v23 offset:4096
	ds_read_b128 v[0:3], v23 offset:4112
	s_add_i32 s18, s4, 2
	s_ashr_i32 s19, s18, 31
	s_lshl_b64 s[18:19], s[18:19], 11
	s_waitcnt lgkmcnt(1)
	v_mov_b32_e32 v14, v5
	v_mov_b32_e32 v15, v6
	v_mov_b32_e32 v16, v4
	v_mov_b32_e32 v17, v7
	v_pk_add_f32 v[14:15], v[14:15], v[16:17]
	s_waitcnt lgkmcnt(0)
; __device__ __forceinline__ u32x4 pack8(const f32x4 v0, const f32x4 v1) { u32x4 w; w.x = cvt_pk_bf16(v0[0], v0[1]); w.y = cvt_pk_bf16(v0[2], v0[3]); w.z = cvt_pk_bf16(v1[0], v1[1]); w.w = cvt_pk_bf16(v1[2], v1[3]); return w; }
; __device__ __forceinline__ float silu_fast(float x) { return x * __builtin_amdgcn_rcpf(1.f + __expf(-x)); }
; #define LAS __attribute__((address_space(3)))
; __device__ __forceinline__ void conv_phase(LAS unsigned char* lds, const bf16_t* PROJ, const float* cw, const float* cb, const float* lg, const float* lb, bf16_t* MIXIN, int G, int tid) {
;     ...
;         for (int q = 0; q < 4; ++q) { const int tt = 4 * wave + q;
;             f32x4 a = *(const LAS f32x4*)(U + tt * 512 + 8 * lane), b = *(const LAS f32x4*)(U + tt * 512 + 8 * lane + 4);
;             const float mean = wave_sum((a[0] + a[1]) + (a[2] + a[3]) + (b[0] + b[1]) + (b[2] + b[3])) * (1.f / 512.f);
;             a = a - mean; b = b - mean;
;             const float var = wave_sum((a[0] * a[0] + a[1] * a[1]) + (a[2] * a[2] + a[3] * a[3]) + (b[0] * b[0] + b[1] * b[1]) + (b[2] * b[2] + b[3] * b[3])) * (1.f / 512.f);
;             const float rstd = rsqrtf(var + LN_EPS);
;             a = a * rstd * *(const f32x4*)(lg + 8 * lane) + *(const f32x4*)(lb + 8 * lane); b = b * rstd * *(const f32x4*)(lg + 8 * lane + 4) + *(const f32x4*)(lb + 8 * lane + 4);
; #pragma unroll
;             for (int x = 0; x < 4; ++x) { a[x] = pg8::silu_fast(a[x]); b[x] = pg8::silu_fast(b[x]); }
;             *(u32x4*)(MIXIN + (size_t)(row0 + tt) * D + 8 * lane) = pg8::pack8(a, b); }
	v_mov_b32_e32 v16, v2
	v_mov_b32_e32 v17, v0
	v_mov_b32_e32 v24, v3
	v_mov_b32_e32 v25, v1
	v_pk_add_f32 v[16:17], v[16:17], v[24:25]
	v_add_f32_e32 v12, v14, v15
	v_add_f32_e32 v12, v12, v17
	v_add_f32_e32 v12, v16, v12
	s_add_i32 s4, s4, 3
	s_ashr_i32 s5, s4, 31
	s_lshl_b64 s[4:5], s[4:5], 11
	s_nop 1
	v_add_f32_dpp v14, v12, v12 quad_perm:[1,0,3,2] row_mask:0xf bank_mask:0xf
	s_nop 1
	v_add_f32_dpp v12, v14, v14 quad_perm:[2,3,0,1] row_mask:0xf bank_mask:0xf
	s_nop 1
	v_add_f32_dpp v14, v12, v12 row_half_mirror row_mask:0xf bank_mask:0xf
	s_nop 1
	v_add_f32_dpp v12, v14, v14 row_mirror row_mask:0xf bank_mask:0xf
	s_nop 0
	v_readlane_b32 s14, v12, 0
	v_readlane_b32 s15, v12, 16
	v_readlane_b32 s16, v12, 32
	v_readlane_b32 s17, v12, 48
	s_nop 1
	v_mov_b32_e32 v14, s15
	v_add_f32_e32 v14, s14, v14
	v_mov_b32_e32 v12, s17
	v_add_f32_e32 v12, s16, v12
	v_add_f32_e32 v12, v14, v12
	v_fmamk_f32 v5, v12, 0xbb000000, v5
	v_fmamk_f32 v4, v12, 0xbb000000, v4
	v_fmamk_f32 v7, v12, 0xbb000000, v7
	v_fmac_f32_e32 v6, 0xbb000000, v12
	v_pk_mul_f32 v[14:15], v[6:7], v[6:7]
	v_pk_mul_f32 v[16:17], v[4:5], v[4:5]
	v_fmamk_f32 v1, v12, 0xbb000000, v1
	v_fmamk_f32 v0, v12, 0xbb000000, v0
	v_fmamk_f32 v3, v12, 0xbb000000, v3
	v_fmac_f32_e32 v2, 0xbb000000, v12
	v_pk_mov_b32 v[24:25], v[16:17], v[14:15] op_sel:[1,0]
	v_mov_b32_e32 v17, v15
	v_pk_add_f32 v[14:15], v[24:25], v[16:17]
	v_pk_mul_f32 v[16:17], v[2:3], v[2:3]
	v_pk_mul_f32 v[24:25], v[0:1], v[0:1]
	v_mov_b32_e32 v26, v16
	v_mov_b32_e32 v27, v24
	v_mov_b32_e32 v24, v17
	v_pk_add_f32 v[16:17], v[26:27], v[24:25]
	v_add_f32_e32 v12, v14, v15
	v_add_f32_e32 v12, v17, v12
	v_add_f32_e32 v12, v16, v12
	s_nop 1
	v_add_f32_dpp v14, v12, v12 quad_perm:[1,0,3,2] row_mask:0xf bank_mask:0xf
	s_nop 1
	v_add_f32_dpp v12, v14, v14 quad_perm:[2,3,0,1] row_mask:0xf bank_mask:0xf
	s_nop 1
	v_add_f32_dpp v14, v12, v12 row_half_mirror row_mask:0xf bank_mask:0xf
	s_nop 1
	v_add_f32_dpp v12, v14, v14 row_mirror row_mask:0xf bank_mask:0xf
	s_nop 0
	v_readlane_b32 s14, v12, 0
	v_readlane_b32 s15, v12, 16
	v_readlane_b32 s16, v12, 32
	v_readlane_b32 s17, v12, 48
	s_nop 1
	v_mov_b32_e32 v14, s15
	v_add_f32_e32 v14, s14, v14
	v_mov_b32_e32 v12, s17
	v_add_f32_e32 v12, s16, v12
	v_add_f32_e32 v12, v14, v12
	v_fmamk_f32 v12, v12, 0x3b000000, v173
	v_cmp_gt_f32_e32 vcc, s81, v12
	v_mul_f32_e32 v14, 0x4b800000, v12
	s_nop 0
	v_cndmask_b32_e32 v12, v12, v14, vcc
	v_rsq_f32_e32 v12, v12
	s_nop 0
	v_mul_f32_e32 v14, 0x45800000, v12
	v_cndmask_b32_e32 v12, v12, v14, vcc
	v_pk_mul_f32 v[14:15], v[4:5], v[12:13] op_sel_hi:[1,0]
	v_pk_mul_f32 v[16:17], v[6:7], v[12:13] op_sel_hi:[1,0]
	v_pk_mul_f32 v[0:1], v[0:1], v[12:13] op_sel_hi:[1,0]
	v_pk_mul_f32 v[2:3], v[2:3], v[12:13] op_sel_hi:[1,0]
	v_pk_fma_f32 v[0:1], v[100:101], v[0:1], v[108:109]
	v_pk_fma_f32 v[2:3], v[102:103], v[2:3], v[110:111]
	v_mul_f32_e32 v5, 0xbfb8aa3b, v0
	v_mul_f32_e32 v6, 0xbfb8aa3b, v1
	v_mul_f32_e32 v7, 0xbfb8aa3b, v2
	v_exp_f32_e32 v5, v5
	v_exp_f32_e32 v6, v6
	v_exp_f32_e32 v7, v7
	v_pk_fma_f32 v[16:17], v[106:107], v[16:17], v[114:115]
	v_add_f32_e32 v5, 1.0, v5
	v_add_f32_e32 v6, 1.0, v6
	v_add_f32_e32 v7, 1.0, v7
	v_rcp_f32_e32 v5, v5
	v_rcp_f32_e32 v6, v6
	v_rcp_f32_e32 v7, v7
	v_pk_fma_f32 v[14:15], v[104:105], v[14:15], v[112:113]
	v_mul_f32_e32 v5, v0, v5
	v_mul_f32_e32 v4, 0xbfb8aa3b, v14
	v_mul_f32_e32 v0, 0xbfb8aa3b, v15
	v_mul_f32_e32 v6, v1, v6
	v_mul_f32_e32 v1, 0xbfb8aa3b, v16
	v_mul_f32_e32 v7, v2, v7
	v_mul_f32_e32 v2, 0xbfb8aa3b, v17
	v_exp_f32_e32 v4, v4
	v_exp_f32_e32 v0, v0
	v_exp_f32_e32 v1, v1
	v_exp_f32_e32 v2, v2
	v_mul_f32_e32 v12, 0xbfb8aa3b, v3
	v_exp_f32_e32 v12, v12
	v_add_f32_e32 v4, 1.0, v4
	v_add_f32_e32 v0, 1.0, v0
	v_add_f32_e32 v1, 1.0, v1
	v_add_f32_e32 v2, 1.0, v2
	v_rcp_f32_e32 v4, v4
	v_rcp_f32_e32 v0, v0
	v_rcp_f32_e32 v1, v1
	v_rcp_f32_e32 v2, v2
	v_add_f32_e32 v12, 1.0, v12
	v_rcp_f32_e32 v12, v12
	v_mul_f32_e32 v4, v14, v4
	v_mul_f32_e32 v0, v15, v0
	v_mul_f32_e32 v1, v16, v1
	v_mul_f32_e32 v2, v17, v2
	v_mul_f32_e32 v3, v3, v12
	v_cvt_pk_bf16_f32 v0, v4, v0
	v_cvt_pk_bf16_f32 v1, v1, v2
	v_cvt_pk_bf16_f32 v2, v5, v6
	v_lshl_add_u64 v[4:5], v[10:11], 0, s[18:19]
	v_cvt_pk_bf16_f32 v3, v7, v3
	global_store_dwordx4 v[4:5], v[0:3], off
	ds_read_b128 v[4:7], v23 offset:6144
	ds_read_b128 v[0:3], v23 offset:6160
	s_waitcnt lgkmcnt(1)
; __device__ __forceinline__ u32x4 pack8(const f32x4 v0, const f32x4 v1) { u32x4 w; w.x = cvt_pk_bf16(v0[0], v0[1]); w.y = cvt_pk_bf16(v0[2], v0[3]); w.z = cvt_pk_bf16(v1[0], v1[1]); w.w = cvt_pk_bf16(v1[2], v1[3]); return w; }
; __device__ __forceinline__ float silu_fast(float x) { return x * __builtin_amdgcn_rcpf(1.f + __expf(-x)); }
; #define LAS __attribute__((address_space(3)))
; __device__ __forceinline__ void conv_phase(LAS unsigned char* lds, const bf16_t* PROJ, const float* cw, const float* cb, const float* lg, const float* lb, bf16_t* MIXIN, int G, int tid) {
;     ...
;         for (int q = 0; q < 4; ++q) { const int tt = 4 * wave + q;
;             f32x4 a = *(const LAS f32x4*)(U + tt * 512 + 8 * lane), b = *(const LAS f32x4*)(U + tt * 512 + 8 * lane + 4);
;             const float mean = wave_sum((a[0] + a[1]) + (a[2] + a[3]) + (b[0] + b[1]) + (b[2] + b[3])) * (1.f / 512.f);
;             a = a - mean; b = b - mean;
;             const float var = wave_sum((a[0] * a[0] + a[1] * a[1]) + (a[2] * a[2] + a[3] * a[3]) + (b[0] * b[0] + b[1] * b[1]) + (b[2] * b[2] + b[3] * b[3])) * (1.f / 512.f);
;             const float rstd = rsqrtf(var + LN_EPS);
;             a = a * rstd * *(const f32x4*)(lg + 8 * lane) + *(const f32x4*)(lb + 8 * lane); b = b * rstd * *(const f32x4*)(lg + 8 * lane + 4) + *(const f32x4*)(lb + 8 * lane + 4);
; #pragma unroll
;             for (int x = 0; x < 4; ++x) { a[x] = pg8::silu_fast(a[x]); b[x] = pg8::silu_fast(b[x]); }
;             *(u32x4*)(MIXIN + (size_t)(row0 + tt) * D + 8 * lane) = pg8::pack8(a, b); }
;         __syncthreads();
	v_mov_b32_e32 v14, v5
	v_mov_b32_e32 v15, v6
	v_mov_b32_e32 v16, v4
	v_mov_b32_e32 v17, v7
	v_pk_add_f32 v[14:15], v[14:15], v[16:17]
	s_waitcnt lgkmcnt(0)
	v_mov_b32_e32 v16, v2
	v_mov_b32_e32 v17, v0
	v_mov_b32_e32 v24, v3
	v_mov_b32_e32 v25, v1
	v_pk_add_f32 v[16:17], v[16:17], v[24:25]
	v_add_f32_e32 v12, v14, v15
	v_add_f32_e32 v12, v12, v17
	v_add_f32_e32 v12, v16, v12
	s_nop 1
	v_add_f32_dpp v14, v12, v12 quad_perm:[1,0,3,2] row_mask:0xf bank_mask:0xf
	s_nop 1
	v_add_f32_dpp v12, v14, v14 quad_perm:[2,3,0,1] row_mask:0xf bank_mask:0xf
	s_nop 1
	v_add_f32_dpp v14, v12, v12 row_half_mirror row_mask:0xf bank_mask:0xf
	s_nop 1
	v_add_f32_dpp v12, v14, v14 row_mirror row_mask:0xf bank_mask:0xf
	s_nop 0
	v_readlane_b32 s14, v12, 0
	v_readlane_b32 s15, v12, 16
	v_readlane_b32 s16, v12, 32
	v_readlane_b32 s17, v12, 48
	s_nop 1
	v_mov_b32_e32 v14, s15
	v_add_f32_e32 v14, s14, v14
	v_mov_b32_e32 v12, s17
	v_add_f32_e32 v12, s16, v12
	v_add_f32_e32 v12, v14, v12
	v_fmamk_f32 v5, v12, 0xbb000000, v5
	v_fmamk_f32 v4, v12, 0xbb000000, v4
	v_fmamk_f32 v7, v12, 0xbb000000, v7
	v_fmac_f32_e32 v6, 0xbb000000, v12
	v_pk_mul_f32 v[14:15], v[6:7], v[6:7]
	v_pk_mul_f32 v[16:17], v[4:5], v[4:5]
	v_fmamk_f32 v1, v12, 0xbb000000, v1
	v_fmamk_f32 v0, v12, 0xbb000000, v0
	v_fmamk_f32 v3, v12, 0xbb000000, v3
	v_fmac_f32_e32 v2, 0xbb000000, v12
	v_pk_mov_b32 v[24:25], v[16:17], v[14:15] op_sel:[1,0]
	v_mov_b32_e32 v17, v15
	v_pk_add_f32 v[14:15], v[24:25], v[16:17]
	v_pk_mul_f32 v[16:17], v[2:3], v[2:3]
	v_pk_mul_f32 v[24:25], v[0:1], v[0:1]
	v_mov_b32_e32 v26, v16
	v_mov_b32_e32 v27, v24
	v_mov_b32_e32 v24, v17
	v_pk_add_f32 v[16:17], v[26:27], v[24:25]
	v_add_f32_e32 v12, v14, v15
	v_add_f32_e32 v12, v17, v12
	v_add_f32_e32 v12, v16, v12
	s_nop 1
	v_add_f32_dpp v13, v12, v12 quad_perm:[1,0,3,2] row_mask:0xf bank_mask:0xf
	s_nop 1
	v_add_f32_dpp v12, v13, v13 quad_perm:[2,3,0,1] row_mask:0xf bank_mask:0xf
	s_nop 1
	v_add_f32_dpp v13, v12, v12 row_half_mirror row_mask:0xf bank_mask:0xf
	s_nop 1
	v_add_f32_dpp v12, v13, v13 row_mirror row_mask:0xf bank_mask:0xf
	s_nop 0
	v_readlane_b32 s14, v12, 0
	v_readlane_b32 s15, v12, 16
	v_readlane_b32 s16, v12, 32
	v_readlane_b32 s17, v12, 48
	s_nop 1
	v_mov_b32_e32 v13, s15
	v_add_f32_e32 v13, s14, v13
	v_mov_b32_e32 v12, s17
	v_add_f32_e32 v12, s16, v12
	v_add_f32_e32 v12, v13, v12
	v_fmamk_f32 v12, v12, 0x3b000000, v173
	v_cmp_gt_f32_e32 vcc, s81, v12
	v_mul_f32_e32 v13, 0x4b800000, v12
	s_nop 0
	v_cndmask_b32_e32 v12, v12, v13, vcc
	v_rsq_f32_e32 v12, v12
	s_nop 0
	v_mul_f32_e32 v13, 0x45800000, v12
	v_cndmask_b32_e32 v12, v12, v13, vcc
	v_pk_mul_f32 v[14:15], v[4:5], v[12:13] op_sel_hi:[1,0]
	v_pk_mul_f32 v[16:17], v[6:7], v[12:13] op_sel_hi:[1,0]
	v_pk_mul_f32 v[0:1], v[0:1], v[12:13] op_sel_hi:[1,0]
	v_pk_mul_f32 v[2:3], v[2:3], v[12:13] op_sel_hi:[1,0]
	v_pk_fma_f32 v[0:1], v[100:101], v[0:1], v[108:109]
	v_pk_fma_f32 v[2:3], v[102:103], v[2:3], v[110:111]
	v_mul_f32_e32 v5, 0xbfb8aa3b, v0
	v_mul_f32_e32 v6, 0xbfb8aa3b, v1
	v_mul_f32_e32 v7, 0xbfb8aa3b, v2
	v_exp_f32_e32 v5, v5
	v_exp_f32_e32 v6, v6
	v_exp_f32_e32 v7, v7
	v_pk_fma_f32 v[16:17], v[106:107], v[16:17], v[114:115]
	v_add_f32_e32 v5, 1.0, v5
	v_add_f32_e32 v6, 1.0, v6
	v_add_f32_e32 v7, 1.0, v7
	v_rcp_f32_e32 v5, v5
	v_rcp_f32_e32 v6, v6
	v_rcp_f32_e32 v7, v7
	v_pk_fma_f32 v[14:15], v[104:105], v[14:15], v[112:113]
	v_mul_f32_e32 v5, v0, v5
	v_mul_f32_e32 v4, 0xbfb8aa3b, v14
	v_mul_f32_e32 v0, 0xbfb8aa3b, v15
	v_mul_f32_e32 v6, v1, v6
	v_mul_f32_e32 v1, 0xbfb8aa3b, v16
	v_mul_f32_e32 v7, v2, v7
	v_mul_f32_e32 v2, 0xbfb8aa3b, v17
	v_exp_f32_e32 v4, v4
	v_exp_f32_e32 v0, v0
	v_exp_f32_e32 v1, v1
	v_exp_f32_e32 v2, v2
	v_mul_f32_e32 v9, 0xbfb8aa3b, v3
	v_exp_f32_e32 v9, v9
	v_add_f32_e32 v4, 1.0, v4
	v_add_f32_e32 v0, 1.0, v0
	v_add_f32_e32 v1, 1.0, v1
	v_add_f32_e32 v2, 1.0, v2
	v_rcp_f32_e32 v4, v4
	v_rcp_f32_e32 v0, v0
	v_rcp_f32_e32 v1, v1
	v_rcp_f32_e32 v2, v2
	v_add_f32_e32 v9, 1.0, v9
	v_rcp_f32_e32 v9, v9
	v_mul_f32_e32 v4, v14, v4
	v_mul_f32_e32 v0, v15, v0
	v_mul_f32_e32 v1, v16, v1
	v_mul_f32_e32 v2, v17, v2
	v_cvt_pk_bf16_f32 v0, v4, v0
	v_cvt_pk_bf16_f32 v1, v1, v2
	v_cvt_pk_bf16_f32 v2, v5, v6
	v_lshl_add_u64 v[4:5], v[10:11], 0, s[4:5]
	v_readlane_b32 s4, v253, 9
	s_add_i32 s6, s6, s4
	v_mul_f32_e32 v3, v3, v9
	s_cmpk_lt_i32 s7, 0x400
	v_cvt_pk_bf16_f32 v3, v7, v3
	global_store_dwordx4 v[4:5], v[0:3], off
	s_barrier
	v_readlane_b32 s5, v253, 10
	s_cbranch_scc0 .LBB0_465

; #define INP(k) ({ int k_ = (k); asm volatile("" : "+s"(k_)); a.in[k_]; })
; __device__ __forceinline__ void ln_row_f32(float* io, const float* g, const float* b, int lane) {
;     f32x4* xr = (f32x4*)io + lane;
;     f32x4 v[4]; float s = 0.f;
; #pragma unroll
;     for (int j = 0; j < 4; ++j) { v[j] = xr[64 * j]; s += (v[j].x + v[j].y) + (v[j].z + v[j].w); }
; __global__ void __launch_bounds__(NWAVES * 64) mega(Args a) {
;     ...
;         } else if (p == NPH - 1) {
;             const float* gg = INP(22) + (DEPTH - 1) * D; const float* bb = INP(23) + (DEPTH - 1) * D;
;             for (int m = gw; m < M; m += NGW) ln_row_f32(Y + (size_t)m * D, gg, bb, lane);
.LBB0_745:
	s_and_b64 vcc, exec, s[4:5]
	s_cbranch_vccz .LBB0_749
	v_readlane_b32 s8, v251, 30
	v_readlane_b32 s9, v251, 31
	s_mov_b32 s6, 22
	s_mov_b32 s4, 23
	s_andn2_b64 vcc, exec, s[8:9]
	s_cbranch_vccnz .LBB0_749
	s_waitcnt vmcnt(0)
	v_and_b32_e32 v0, 64, v230
	v_add_u32_e32 v0, 64, v0
	s_waitcnt lgkmcnt(0)
	v_xor_b32_e32 v1, 1, v230
	v_cmp_lt_i32_e32 vcc, v1, v0
	s_ashr_i32 s7, s6, 31
	s_lshl_b64 s[6:7], s[6:7], 3
	v_cndmask_b32_e32 v1, v230, v1, vcc
	v_lshlrev_b32_e32 v37, 2, v1
	v_xor_b32_e32 v1, 2, v230
	v_cmp_lt_i32_e32 vcc, v1, v0
	s_add_u32 s6, s0, s6
	s_addc_u32 s7, s1, s7
	v_cndmask_b32_e32 v1, v230, v1, vcc
	v_lshlrev_b32_e32 v44, 2, v1
	v_xor_b32_e32 v1, 4, v230
	s_ashr_i32 s5, s4, 31
	v_cmp_lt_i32_e32 vcc, v1, v0
	s_lshl_b64 s[4:5], s[4:5], 3
	s_add_u32 s4, s0, s4
	v_cndmask_b32_e32 v1, v230, v1, vcc
	v_lshlrev_b32_e32 v45, 2, v1
	v_xor_b32_e32 v1, 8, v230
	s_addc_u32 s5, s1, s5
	v_cmp_lt_i32_e32 vcc, v1, v0
	s_load_dwordx2 s[4:5], s[4:5], 0x0
	s_nop 0
	s_load_dwordx2 s[6:7], s[6:7], 0x0
	v_cndmask_b32_e32 v1, v230, v1, vcc
	v_lshlrev_b32_e32 v46, 2, v1
	v_xor_b32_e32 v1, 16, v230
	v_cmp_lt_i32_e32 vcc, v1, v0
	s_waitcnt lgkmcnt(0)
	s_add_u32 s4, s4, 0x3000
	s_addc_u32 s5, s5, 0
	v_cndmask_b32_e32 v1, v230, v1, vcc
	v_lshlrev_b32_e32 v47, 2, v1
	v_xor_b32_e32 v1, 32, v230
	v_cmp_lt_i32_e32 vcc, v1, v0
	s_add_u32 s6, s6, 0x3000
	v_lshlrev_b32_e32 v164, 4, v172
	v_cndmask_b32_e32 v0, v230, v1, vcc
	s_addc_u32 s7, s7, 0
	v_lshlrev_b32_e32 v48, 2, v0
	v_or_b32_e32 v0, 0x400, v164
	v_mov_b32_e32 v1, v165
	v_lshl_add_u64 v[20:21], s[6:7], 0, v[0:1]
	v_lshl_add_u64 v[22:23], s[4:5], 0, v[0:1]
	v_or_b32_e32 v0, 0x800, v164
	v_lshl_add_u64 v[24:25], s[6:7], 0, v[0:1]
	v_lshl_add_u64 v[26:27], s[4:5], 0, v[0:1]
	v_or_b32_e32 v0, 0xc00, v164
	v_lshl_add_u64 v[18:19], s[4:5], 0, v[164:165]
	v_lshl_add_u64 v[30:31], s[4:5], 0, v[0:1]
	v_readlane_b32 s4, v253, 33
	v_readlane_b32 s5, v253, 34
	v_lshl_add_u64 v[16:17], s[6:7], 0, v[164:165]
	v_lshl_add_u64 v[28:29], s[6:7], 0, v[0:1]
	v_lshl_add_u64 v[32:33], s[4:5], 0, v[164:165]
	v_readlane_b32 s4, v253, 11
	v_readlane_b32 s5, v253, 12
	v_writelane_b32 v255, s14, 46
	v_writelane_b32 v255, s15, 47
	v_writelane_b32 v255, s16, 48
	v_writelane_b32 v255, s17, 49
	global_load_dwordx4 v[180:183], v[16:17], off
	global_load_dwordx4 v[184:187], v[18:19], off
	global_load_dwordx4 v[188:191], v[20:21], off
	global_load_dwordx4 v[192:195], v[22:23], off
	global_load_dwordx4 v[196:199], v[24:25], off
	global_load_dwordx4 v[200:203], v[26:27], off
	global_load_dwordx4 v[204:207], v[28:29], off
	global_load_dwordx4 v[208:211], v[30:31], off
	s_waitcnt vmcnt(0)
	global_load_dwordx4 v[52:55], v[32:33], off offset:-2048
	global_load_dwordx4 v[56:59], v[32:33], off offset:-1024
	global_load_dwordx4 v[60:63], v[32:33], off
	global_load_dwordx4 v[64:67], v[32:33], off offset:1024
	s_waitcnt vmcnt(0)

; __device__ __forceinline__ void ln_row_f32(float* io, const float* g, const float* b, int lane) {
;     f32x4* xr = (f32x4*)io + lane;
;     f32x4 v[4]; float s = 0.f;
; #pragma unroll
;     for (int j = 0; j < 4; ++j) { v[j] = xr[64 * j]; s += (v[j].x + v[j].y) + (v[j].z + v[j].w); }
;     const float mean = wave_sum(s) * (1.f / D); float s2 = 0.f;
; #pragma unroll
;     for (int j = 0; j < 4; ++j) { v[j] = v[j] - mean; s2 += (v[j].x * v[j].x + v[j].y * v[j].y) + (v[j].z * v[j].z + v[j].w * v[j].w); }
;     const float rstd = rsqrtf(wave_sum(s2) * (1.f / D) + LN_EPS);
; #pragma unroll
;     for (int j = 0; j < 4; ++j) { const int c = (64 * j + lane) * 4; xr[64 * j] = v[j] * rstd * *(const f32x4*)(g + c) + *(const f32x4*)(b + c); }
; }
.Lfln_nopf:
	v_add_f32_e32 v40, v8, v9
	v_add_f32_e32 v42, v10, v11
	v_mov_b32_e32 v35, v0
	v_mov_b32_e32 v39, v1
	v_mov_b32_e32 v41, v2
	v_mov_b32_e32 v43, v3
	v_pk_add_f32 v[34:35], v[34:35], v[38:39]
	v_pk_add_f32 v[38:39], v[40:41], v[42:43]
	s_nop 0
	v_pk_add_f32 v[34:35], v[34:35], v[38:39]
	s_nop 0
	v_add_f32_e32 v34, v34, v35
	s_nop 1
	v_add_f32_dpp v35, v34, v34 quad_perm:[1,0,3,2] row_mask:0xf bank_mask:0xf
	s_nop 1
	v_add_f32_dpp v34, v35, v35 quad_perm:[2,3,0,1] row_mask:0xf bank_mask:0xf
	s_nop 1
	v_add_f32_dpp v35, v34, v34 row_half_mirror row_mask:0xf bank_mask:0xf
	s_nop 1
	v_add_f32_dpp v34, v35, v35 row_mirror row_mask:0xf bank_mask:0xf
	s_nop 0
	v_readlane_b32 s14, v34, 0
	v_readlane_b32 s15, v34, 16
	v_readlane_b32 s16, v34, 32
	v_readlane_b32 s17, v34, 48
	s_nop 1
	v_mov_b32_e32 v35, s15
	v_add_f32_e32 v35, s14, v35
	v_mov_b32_e32 v34, s17
	v_add_f32_e32 v34, s16, v34
	v_add_f32_e32 v36, v35, v34
	v_fmamk_f32 v13, v36, 0xba800000, v13
	v_fmamk_f32 v12, v36, 0xba800000, v12
	v_fmamk_f32 v15, v36, 0xba800000, v15
	v_fmac_f32_e32 v14, 0xba800000, v36
	v_pk_mul_f32 v[34:35], v[14:15], v[14:15]
	v_pk_mul_f32 v[38:39], v[12:13], v[12:13]
	v_fmamk_f32 v7, v36, 0xba800000, v7
	v_pk_mov_b32 v[40:41], v[38:39], v[34:35] op_sel:[1,0]
	v_mov_b32_e32 v39, v35
	v_pk_add_f32 v[34:35], v[40:41], v[38:39]
	v_fmamk_f32 v39, v36, 0xba800000, v5
	v_fmamk_f32 v38, v36, 0xba800000, v4
	v_fmac_f32_e32 v6, 0xba800000, v36
	v_pk_add_f32 v[40:41], v[34:35], v[34:35] op_sel_hi:[0,1]
	v_pk_mul_f32 v[4:5], v[6:7], v[6:7]
	v_pk_mul_f32 v[34:35], v[38:39], v[38:39]
	v_fmac_f32_e32 v10, 0xba800000, v36
	v_pk_mov_b32 v[42:43], v[34:35], v[4:5] op_sel:[1,0]
	v_mov_b32_e32 v35, v5
	v_pk_add_f32 v[4:5], v[42:43], v[34:35]
	v_fmamk_f32 v34, v36, 0xba800000, v8
	v_pk_add_f32 v[4:5], v[4:5], v[4:5] op_sel_hi:[0,1]
	v_fmamk_f32 v35, v36, 0xba800000, v9
	v_mul_f32_e32 v4, v34, v34
	v_fmamk_f32 v11, v36, 0xba800000, v11
	v_pk_fma_f32 v[42:43], v[34:35], v[34:35], v[4:5] op_sel_hi:[1,1,0]
	v_mul_f32_e32 v4, v10, v10
	v_pk_fma_f32 v[50:51], v[10:11], v[10:11], v[4:5] op_sel_hi:[1,1,0]
	v_fmamk_f32 v9, v36, 0xba800000, v3
	v_fmamk_f32 v8, v36, 0xba800000, v2
	v_fmamk_f32 v1, v36, 0xba800000, v1
	v_fmac_f32_e32 v0, 0xba800000, v36
	v_mul_f32_e32 v42, v0, v0
	v_mul_f32_e32 v50, v1, v1
	v_mul_f32_e32 v40, v8, v8
	v_mul_f32_e32 v4, v9, v9
	v_pk_add_f32 v[2:3], v[42:43], v[50:51]
	v_pk_add_f32 v[4:5], v[40:41], v[4:5]
	s_nop 0
	v_pk_add_f32 v[2:3], v[2:3], v[4:5]
	s_nop 0
	v_add_f32_e32 v2, v2, v3
	s_nop 1
	v_add_f32_dpp v3, v2, v2 quad_perm:[1,0,3,2] row_mask:0xf bank_mask:0xf
	s_nop 1
	v_add_f32_dpp v2, v3, v3 quad_perm:[2,3,0,1] row_mask:0xf bank_mask:0xf
	s_nop 1
	v_add_f32_dpp v3, v2, v2 row_half_mirror row_mask:0xf bank_mask:0xf
	s_nop 1
	v_add_f32_dpp v2, v3, v3 row_mirror row_mask:0xf bank_mask:0xf
	s_nop 0
	v_readlane_b32 s14, v2, 0
	v_readlane_b32 s15, v2, 16
	v_readlane_b32 s16, v2, 32
	v_readlane_b32 s17, v2, 48
	s_nop 1
	v_mov_b32_e32 v3, s15
	v_add_f32_e32 v3, s14, v3
	v_mov_b32_e32 v2, s17
	v_add_f32_e32 v2, s16, v2
	v_add_f32_e32 v2, v3, v2
	v_fmamk_f32 v2, v2, 0x3a800000, v173
	v_cmp_gt_f32_e32 vcc, s81, v2
	v_mul_f32_e32 v3, 0x4b800000, v2
	s_nop 0
	v_cndmask_b32_e32 v2, v2, v3, vcc
	v_rsq_f32_e32 v2, v2
	s_nop 0
	v_mul_f32_e32 v3, 0x45800000, v2
	v_cndmask_b32_e32 v36, v2, v3, vcc
	v_pk_mul_f32 v[40:41], v[12:13], v[36:37] op_sel_hi:[1,0]
	v_pk_mul_f32 v[42:43], v[14:15], v[36:37] op_sel_hi:[1,0]
	v_pk_mul_f32 v[6:7], v[6:7], v[36:37] op_sel_hi:[1,0]
	v_pk_mul_f32 v[38:39], v[38:39], v[36:37] op_sel_hi:[1,0]
	v_pk_mul_f32 v[8:9], v[8:9], v[36:37] op_sel_hi:[1,0]
	v_pk_fma_f32 v[4:5], v[182:183], v[42:43], v[186:187]
	v_pk_fma_f32 v[2:3], v[180:181], v[40:41], v[184:185]
	global_store_dwordx4 v[32:33], v[2:5], off offset:-2048
	s_nop 1
	v_pk_fma_f32 v[2:3], v[188:189], v[38:39], v[192:193]
	v_pk_fma_f32 v[4:5], v[190:191], v[6:7], v[194:195]
	global_store_dwordx4 v[32:33], v[2:5], off offset:-1024
	v_pk_mul_f32 v[6:7], v[10:11], v[36:37] op_sel_hi:[1,0]
	v_pk_mul_f32 v[14:15], v[34:35], v[36:37] op_sel_hi:[1,0]
	s_nop 0
	v_pk_fma_f32 v[4:5], v[198:199], v[6:7], v[202:203]
	v_pk_fma_f32 v[2:3], v[196:197], v[14:15], v[200:201]
	global_store_dwordx4 v[32:33], v[2:5], off
	v_pk_mul_f32 v[10:11], v[0:1], v[36:37] op_sel_hi:[1,0]
	s_nop 0
	v_pk_fma_f32 v[0:1], v[204:205], v[10:11], v[208:209]
	v_pk_fma_f32 v[2:3], v[206:207], v[8:9], v[210:211]
	global_store_dwordx4 v[32:33], v[0:3], off offset:1024
	v_lshl_add_u64 v[32:33], v[32:33], 0, s[94:95]
	s_cbranch_scc0 .LBB0_748
	v_readlane_b32 s14, v255, 46
	v_readlane_b32 s15, v255, 47
	v_readlane_b32 s16, v255, 48
	v_readlane_b32 s17, v255, 49
	s_nop 1
